# mlp1: epilogue deferred past next-tile prologue loads (vmcnt(16)), hand-written last k-tile + EPI-0/2 epilogues
# speedup vs baseline: 1.0048x; 1.0020x over previous
.Lmt4_tail_0:
	s_add_i32 s55, s55, s24
	s_cmp_lt_u32 s55, s22
	s_cbranch_scc0 .LBB0_293

.LBB0_302:
	ds_read_b128 v[216:219], v176 offset:36864
	ds_read_b128 v[200:203], v188
	ds_read_b128 v[220:223], v176 offset:41472
	ds_read_b128 v[204:207], v188 offset:4608
	ds_read_b128 v[208:211], v188 offset:9216
	ds_read_b128 v[212:215], v187
	s_waitcnt lgkmcnt(4)
	v_mfma_f32_32x32x16_bf16 v[112:127], v[200:203], v[216:219], v[112:127]
	ds_read_b128 v[240:243], v176 offset:36896
	global_load_dwordx4 v[140:143], v190, s[42:43]
	s_waitcnt lgkmcnt(4)
	v_mfma_f32_32x32x16_bf16 v[96:111], v[200:203], v[220:223], v[96:111]
	ds_read_b128 v[224:227], v188 offset:32
	global_load_dwordx4 v[164:167], v190, s[40:41]
	s_waitcnt lgkmcnt(4)
	v_mfma_f32_32x32x16_bf16 v[80:95], v[204:207], v[216:219], v[80:95]
	ds_read_b128 v[244:247], v176 offset:41504
	global_load_dwordx4 v[128:131], v191, s[40:41]
	s_waitcnt lgkmcnt(5)
	v_mfma_f32_32x32x16_bf16 v[64:79], v[204:207], v[220:223], v[64:79]
	ds_read_b128 v[228:231], v188 offset:4640
	global_load_dwordx4 v[132:135], v192, s[40:41]
	s_waitcnt lgkmcnt(5)
	v_mfma_f32_32x32x16_bf16 v[48:63], v[208:211], v[216:219], v[48:63]
	ds_read_b128 v[232:235], v188 offset:9248
	global_load_dwordx4 v[136:139], v193, s[40:41]
	s_waitcnt lgkmcnt(6)
	v_mfma_f32_32x32x16_bf16 v[32:47], v[208:211], v[220:223], v[32:47]
	ds_read_b128 v[236:239], v187 offset:32
	global_load_dwordx4 v[144:147], v194, s[40:41]
	s_waitcnt lgkmcnt(6)
	v_mfma_f32_32x32x16_bf16 v[16:31], v[212:215], v[216:219], v[16:31]
	global_load_dwordx4 v[148:151], v195, s[40:41]
	global_load_dwordx4 v[152:155], v196, s[40:41]
	s_waitcnt lgkmcnt(6)
	v_mfma_f32_32x32x16_bf16 v[0:15], v[212:215], v[220:223], v[0:15]
	global_load_dwordx4 v[156:159], v197, s[40:41]
	global_load_dwordx4 v[160:163], v191, s[42:43]
	s_waitcnt lgkmcnt(4)
	v_mfma_f32_32x32x16_bf16 v[112:127], v[224:227], v[240:243], v[112:127]
	ds_read_b128 v[200:203], v188 offset:64
	global_load_dwordx4 v[168:171], v192, s[42:43]
	s_waitcnt lgkmcnt(4)
	v_mfma_f32_32x32x16_bf16 v[96:111], v[224:227], v[244:247], v[96:111]
	ds_read_b128 v[204:207], v188 offset:4672
	global_load_dwordx4 v[172:175], v193, s[42:43]
	s_add_u32 s40, s40, 0x80
	s_addc_u32 s41, s41, 0
	s_add_u32 s42, s42, 0x80
	s_addc_u32 s43, s43, 0
	s_add_u32 s16, s16, 0x80
	s_waitcnt lgkmcnt(4)
	v_mfma_f32_32x32x16_bf16 v[80:95], v[228:231], v[240:243], v[80:95]
	ds_read_b128 v[208:211], v188 offset:9280
	s_waitcnt lgkmcnt(5)
	v_mfma_f32_32x32x16_bf16 v[64:79], v[228:231], v[244:247], v[64:79]
	ds_read_b128 v[212:215], v187 offset:64
	s_waitcnt lgkmcnt(5)
	v_mfma_f32_32x32x16_bf16 v[48:63], v[232:235], v[240:243], v[48:63]
	ds_read_b128 v[216:219], v176 offset:36928
	s_waitcnt lgkmcnt(6)
	v_mfma_f32_32x32x16_bf16 v[32:47], v[232:235], v[244:247], v[32:47]
	ds_read_b128 v[220:223], v176 offset:41536
	s_waitcnt lgkmcnt(6)
	v_mfma_f32_32x32x16_bf16 v[16:31], v[236:239], v[240:243], v[16:31]
	s_waitcnt lgkmcnt(6)
	v_mfma_f32_32x32x16_bf16 v[0:15], v[236:239], v[244:247], v[0:15]
	s_waitcnt lgkmcnt(1)
	v_mfma_f32_32x32x16_bf16 v[112:127], v[200:203], v[216:219], v[112:127]
	ds_read_b128 v[224:227], v188 offset:96
	s_waitcnt lgkmcnt(1)
	v_mfma_f32_32x32x16_bf16 v[96:111], v[200:203], v[220:223], v[96:111]
	ds_read_b128 v[228:231], v188 offset:4704
	s_waitcnt lgkmcnt(3)
	v_mfma_f32_32x32x16_bf16 v[80:95], v[204:207], v[216:219], v[80:95]
	ds_read_b128 v[232:235], v188 offset:9312
	s_waitcnt lgkmcnt(3)
	v_mfma_f32_32x32x16_bf16 v[64:79], v[204:207], v[220:223], v[64:79]
	ds_read_b128 v[236:239], v187 offset:96
	s_waitcnt lgkmcnt(5)
	v_mfma_f32_32x32x16_bf16 v[48:63], v[208:211], v[216:219], v[48:63]
	ds_read_b128 v[240:243], v176 offset:36960
	s_waitcnt lgkmcnt(5)
	v_mfma_f32_32x32x16_bf16 v[32:47], v[208:211], v[220:223], v[32:47]
	ds_read_b128 v[244:247], v176 offset:41568
	s_waitcnt lgkmcnt(7)
	v_mfma_f32_32x32x16_bf16 v[16:31], v[212:215], v[216:219], v[16:31]
	s_waitcnt lgkmcnt(6)
	v_mfma_f32_32x32x16_bf16 v[0:15], v[212:215], v[220:223], v[0:15]
	s_waitcnt lgkmcnt(0)
	s_barrier
	s_waitcnt vmcnt(0)
	s_waitcnt lgkmcnt(1)
	v_mfma_f32_32x32x16_bf16 v[112:127], v[224:227], v[240:243], v[112:127]
	ds_write_b128 v189, v[164:167]
	ds_write_b128 v189, v[128:131] offset:4608
	s_waitcnt lgkmcnt(2)
	v_mfma_f32_32x32x16_bf16 v[96:111], v[224:227], v[244:247], v[96:111]
	ds_write_b128 v189, v[132:135] offset:9216
	s_waitcnt lgkmcnt(4)
	v_mfma_f32_32x32x16_bf16 v[80:95], v[228:231], v[240:243], v[80:95]
	ds_write_b128 v189, v[136:139] offset:13824
	ds_write_b128 v189, v[144:147] offset:18432
	s_waitcnt lgkmcnt(5)
	v_mfma_f32_32x32x16_bf16 v[64:79], v[228:231], v[244:247], v[64:79]
	ds_write_b128 v189, v[148:151] offset:23040
	s_waitcnt lgkmcnt(7)
	v_mfma_f32_32x32x16_bf16 v[48:63], v[232:235], v[240:243], v[48:63]
	ds_write_b128 v189, v[152:155] offset:27648
	ds_write_b128 v189, v[156:159] offset:32256
	s_waitcnt lgkmcnt(8)
	v_mfma_f32_32x32x16_bf16 v[32:47], v[232:235], v[244:247], v[32:47]
	ds_write_b128 v189, v[140:143] offset:36864
	s_waitcnt lgkmcnt(10)
	v_mfma_f32_32x32x16_bf16 v[16:31], v[236:239], v[240:243], v[16:31]
	ds_write_b128 v189, v[160:163] offset:41472
	ds_write_b128 v189, v[168:171] offset:46080
	s_waitcnt lgkmcnt(11)
	v_mfma_f32_32x32x16_bf16 v[0:15], v[236:239], v[244:247], v[0:15]
	ds_write_b128 v189, v[172:175] offset:50688
	s_waitcnt lgkmcnt(0)
	s_barrier
	s_cmpk_lg_i32 s16, 0x780
	s_cbranch_scc1 .LBB0_302
	ds_read_b128 v[216:219], v176 offset:36864
	ds_read_b128 v[200:203], v188
	ds_read_b128 v[220:223], v176 offset:41472
	ds_read_b128 v[204:207], v188 offset:4608
	ds_read_b128 v[208:211], v188 offset:9216
	ds_read_b128 v[212:215], v187
	s_waitcnt lgkmcnt(4)
	v_mfma_f32_32x32x16_bf16 v[112:127], v[200:203], v[216:219], v[112:127]
	ds_read_b128 v[240:243], v176 offset:36896
	s_waitcnt lgkmcnt(4)
	v_mfma_f32_32x32x16_bf16 v[96:111], v[200:203], v[220:223], v[96:111]
	ds_read_b128 v[224:227], v188 offset:32
	s_waitcnt lgkmcnt(4)
	v_mfma_f32_32x32x16_bf16 v[80:95], v[204:207], v[216:219], v[80:95]
	ds_read_b128 v[244:247], v176 offset:41504
	s_waitcnt lgkmcnt(5)
	v_mfma_f32_32x32x16_bf16 v[64:79], v[204:207], v[220:223], v[64:79]
	ds_read_b128 v[228:231], v188 offset:4640
	s_waitcnt lgkmcnt(5)
	v_mfma_f32_32x32x16_bf16 v[48:63], v[208:211], v[216:219], v[48:63]
	ds_read_b128 v[232:235], v188 offset:9248
	s_waitcnt lgkmcnt(6)
	v_mfma_f32_32x32x16_bf16 v[32:47], v[208:211], v[220:223], v[32:47]
	ds_read_b128 v[236:239], v187 offset:32
	s_waitcnt lgkmcnt(6)
	v_mfma_f32_32x32x16_bf16 v[16:31], v[212:215], v[216:219], v[16:31]
	s_waitcnt lgkmcnt(6)
	v_mfma_f32_32x32x16_bf16 v[0:15], v[212:215], v[220:223], v[0:15]
	s_waitcnt lgkmcnt(4)
	v_mfma_f32_32x32x16_bf16 v[112:127], v[224:227], v[240:243], v[112:127]
	ds_read_b128 v[200:203], v188 offset:64
	s_waitcnt lgkmcnt(4)
	v_mfma_f32_32x32x16_bf16 v[96:111], v[224:227], v[244:247], v[96:111]
	ds_read_b128 v[204:207], v188 offset:4672
	s_waitcnt lgkmcnt(4)
	v_mfma_f32_32x32x16_bf16 v[80:95], v[228:231], v[240:243], v[80:95]
	ds_read_b128 v[208:211], v188 offset:9280
	s_waitcnt lgkmcnt(5)
	v_mfma_f32_32x32x16_bf16 v[64:79], v[228:231], v[244:247], v[64:79]
	ds_read_b128 v[212:215], v187 offset:64
	s_waitcnt lgkmcnt(5)
	v_mfma_f32_32x32x16_bf16 v[48:63], v[232:235], v[240:243], v[48:63]
	ds_read_b128 v[216:219], v176 offset:36928
	s_waitcnt lgkmcnt(6)
	v_mfma_f32_32x32x16_bf16 v[32:47], v[232:235], v[244:247], v[32:47]
	ds_read_b128 v[220:223], v176 offset:41536
	s_waitcnt lgkmcnt(6)
	v_mfma_f32_32x32x16_bf16 v[16:31], v[236:239], v[240:243], v[16:31]
	s_waitcnt lgkmcnt(6)
	v_mfma_f32_32x32x16_bf16 v[0:15], v[236:239], v[244:247], v[0:15]
	s_waitcnt lgkmcnt(1)
	v_mfma_f32_32x32x16_bf16 v[112:127], v[200:203], v[216:219], v[112:127]
	ds_read_b128 v[224:227], v188 offset:96
	s_waitcnt lgkmcnt(1)
	v_mfma_f32_32x32x16_bf16 v[96:111], v[200:203], v[220:223], v[96:111]
	ds_read_b128 v[228:231], v188 offset:4704
	s_waitcnt lgkmcnt(3)
	v_mfma_f32_32x32x16_bf16 v[80:95], v[204:207], v[216:219], v[80:95]
	ds_read_b128 v[232:235], v188 offset:9312
	s_waitcnt lgkmcnt(3)
	v_mfma_f32_32x32x16_bf16 v[64:79], v[204:207], v[220:223], v[64:79]
	ds_read_b128 v[236:239], v187 offset:96
	s_waitcnt lgkmcnt(5)
	v_mfma_f32_32x32x16_bf16 v[48:63], v[208:211], v[216:219], v[48:63]
	ds_read_b128 v[240:243], v176 offset:36960
	s_waitcnt lgkmcnt(5)
	v_mfma_f32_32x32x16_bf16 v[32:47], v[208:211], v[220:223], v[32:47]
	ds_read_b128 v[244:247], v176 offset:41568
	s_waitcnt lgkmcnt(7)
	v_mfma_f32_32x32x16_bf16 v[16:31], v[212:215], v[216:219], v[16:31]
	s_waitcnt lgkmcnt(6)
	v_mfma_f32_32x32x16_bf16 v[0:15], v[212:215], v[220:223], v[0:15]
	s_waitcnt lgkmcnt(1)
	v_mfma_f32_32x32x16_bf16 v[112:127], v[224:227], v[240:243], v[112:127]
	s_waitcnt lgkmcnt(0)
	v_mfma_f32_32x32x16_bf16 v[96:111], v[224:227], v[244:247], v[96:111]
	s_waitcnt lgkmcnt(1)
	v_mfma_f32_32x32x16_bf16 v[80:95], v[228:231], v[240:243], v[80:95]
	s_waitcnt lgkmcnt(0)
	v_mfma_f32_32x32x16_bf16 v[64:79], v[228:231], v[244:247], v[64:79]
	s_waitcnt lgkmcnt(1)
	v_mfma_f32_32x32x16_bf16 v[48:63], v[232:235], v[240:243], v[48:63]
	s_waitcnt lgkmcnt(0)
	v_mfma_f32_32x32x16_bf16 v[32:47], v[232:235], v[244:247], v[32:47]
	s_waitcnt lgkmcnt(1)
	v_mfma_f32_32x32x16_bf16 v[16:31], v[236:239], v[240:243], v[16:31]
	s_waitcnt lgkmcnt(0)
	v_mfma_f32_32x32x16_bf16 v[0:15], v[236:239], v[244:247], v[0:15]
	s_mul_i32 s44, s12, 0x1240
	s_add_u32 s40, s30, s44
	s_addc_u32 s41, s31, 0
	s_lshl_b32 s44, s8, 1
	s_add_u32 s40, s40, s44
	s_addc_u32 s41, s41, 0
	s_add_u32 s40, s40, 0x7157900
	s_addc_u32 s41, s41, 0
	v_and_b32_e32 v131, 15, v182
	v_lshrrev_b32_e32 v172, 4, v182
	v_lshl_add_u32 v130, v131, 3, s8
	s_movk_i32 s44, 0x920
	v_cmp_gt_u32_e64 s[42:43], s44, v130
	v_mul_u32_u24_e32 v164, 0x1240, v172
	v_lshl_add_u32 v164, v131, 4, v164
	v_add_u32_e32 v165, 0x12400, v164
	v_add_u32_e32 v166, 0x24800, v164
	v_add_u32_e32 v167, 0x36c00, v164
	v_add_u32_e32 v168, 0x92000, v164
	v_add_u32_e32 v169, 0xa4400, v164
	v_add_u32_e32 v170, 0xb6800, v164
	v_add_u32_e32 v171, 0xc8c00, v164
	v_mul_u32_u24_e32 v129, 0x110, v172
	v_lshl_add_u32 v129, v131, 4, v129
	v_lshrrev_b32_e32 v131, 7, v182
	v_bfe_u32 v172, v182, 5, 1
	v_lshlrev_b32_e32 v131, 6, v131
	v_lshl_or_b32 v131, v172, 2, v131
	v_mul_u32_u24_e32 v131, 136, v131
	v_and_b32_e32 v172, 0x5f, v182
	v_add_lshl_u32 v128, v131, v172, 1
	s_barrier
	v_cvt_pk_bf16_f32 v112, v112, v113
	v_cvt_pk_bf16_f32 v114, v114, v115
	v_cvt_pk_bf16_f32 v116, v116, v117
	v_cvt_pk_bf16_f32 v118, v118, v119
	v_cvt_pk_bf16_f32 v120, v120, v121
	v_cvt_pk_bf16_f32 v122, v122, v123
	v_cvt_pk_bf16_f32 v124, v124, v125
	v_cvt_pk_bf16_f32 v126, v126, v127
	v_cvt_pk_bf16_f32 v96, v96, v97
	v_cvt_pk_bf16_f32 v98, v98, v99
	v_cvt_pk_bf16_f32 v100, v100, v101
	v_cvt_pk_bf16_f32 v102, v102, v103
	v_cvt_pk_bf16_f32 v104, v104, v105
	v_cvt_pk_bf16_f32 v106, v106, v107
	v_cvt_pk_bf16_f32 v108, v108, v109
	v_cvt_pk_bf16_f32 v110, v110, v111
	v_cvt_pk_bf16_f32 v80, v80, v81
	v_cvt_pk_bf16_f32 v82, v82, v83
	v_cvt_pk_bf16_f32 v84, v84, v85
	v_cvt_pk_bf16_f32 v86, v86, v87
	v_cvt_pk_bf16_f32 v88, v88, v89
	v_cvt_pk_bf16_f32 v90, v90, v91
	v_cvt_pk_bf16_f32 v92, v92, v93
	v_cvt_pk_bf16_f32 v94, v94, v95
	v_cvt_pk_bf16_f32 v64, v64, v65
	v_cvt_pk_bf16_f32 v66, v66, v67
	v_cvt_pk_bf16_f32 v68, v68, v69
	v_cvt_pk_bf16_f32 v70, v70, v71
	v_cvt_pk_bf16_f32 v72, v72, v73
	v_cvt_pk_bf16_f32 v74, v74, v75
	v_cvt_pk_bf16_f32 v76, v76, v77
	v_cvt_pk_bf16_f32 v78, v78, v79
	ds_write_b16 v128, v112
	ds_write_b16_d16_hi v128, v112 offset:272
	ds_write_b16 v128, v114 offset:544
	ds_write_b16_d16_hi v128, v114 offset:816
	ds_write_b16 v128, v116 offset:2176
	ds_write_b16_d16_hi v128, v116 offset:2448
	ds_write_b16 v128, v118 offset:2720
	ds_write_b16_d16_hi v128, v118 offset:2992
	ds_write_b16 v128, v120 offset:4352
	ds_write_b16_d16_hi v128, v120 offset:4624
	ds_write_b16 v128, v122 offset:4896
	ds_write_b16_d16_hi v128, v122 offset:5168
	ds_write_b16 v128, v124 offset:6528
	ds_write_b16_d16_hi v128, v124 offset:6800
	ds_write_b16 v128, v126 offset:7072
	ds_write_b16_d16_hi v128, v126 offset:7344
	ds_write_b16 v128, v96 offset:64
	ds_write_b16_d16_hi v128, v96 offset:336
	ds_write_b16 v128, v98 offset:608
	ds_write_b16_d16_hi v128, v98 offset:880
	ds_write_b16 v128, v100 offset:2240
	ds_write_b16_d16_hi v128, v100 offset:2512
	ds_write_b16 v128, v102 offset:2784
	ds_write_b16_d16_hi v128, v102 offset:3056
	ds_write_b16 v128, v104 offset:4416
	ds_write_b16_d16_hi v128, v104 offset:4688
	ds_write_b16 v128, v106 offset:4960
	ds_write_b16_d16_hi v128, v106 offset:5232
	ds_write_b16 v128, v108 offset:6592
	ds_write_b16_d16_hi v128, v108 offset:6864
	ds_write_b16 v128, v110 offset:7136
	ds_write_b16_d16_hi v128, v110 offset:7408
	ds_write_b16 v128, v80 offset:8704
	ds_write_b16_d16_hi v128, v80 offset:8976
	ds_write_b16 v128, v82 offset:9248
	ds_write_b16_d16_hi v128, v82 offset:9520
	ds_write_b16 v128, v84 offset:10880
	ds_write_b16_d16_hi v128, v84 offset:11152
	ds_write_b16 v128, v86 offset:11424
	ds_write_b16_d16_hi v128, v86 offset:11696
	ds_write_b16 v128, v88 offset:13056
	ds_write_b16_d16_hi v128, v88 offset:13328
	ds_write_b16 v128, v90 offset:13600
	ds_write_b16_d16_hi v128, v90 offset:13872
	ds_write_b16 v128, v92 offset:15232
	ds_write_b16_d16_hi v128, v92 offset:15504
	ds_write_b16 v128, v94 offset:15776
	ds_write_b16_d16_hi v128, v94 offset:16048
	ds_write_b16 v128, v64 offset:8768
	ds_write_b16_d16_hi v128, v64 offset:9040
	ds_write_b16 v128, v66 offset:9312
	ds_write_b16_d16_hi v128, v66 offset:9584
	ds_write_b16 v128, v68 offset:10944
	ds_write_b16_d16_hi v128, v68 offset:11216
	ds_write_b16 v128, v70 offset:11488
	ds_write_b16_d16_hi v128, v70 offset:11760
	ds_write_b16 v128, v72 offset:13120
	ds_write_b16_d16_hi v128, v72 offset:13392
	ds_write_b16 v128, v74 offset:13664
	ds_write_b16_d16_hi v128, v74 offset:13936
	ds_write_b16 v128, v76 offset:15296
	ds_write_b16_d16_hi v128, v76 offset:15568
	ds_write_b16 v128, v78 offset:15840
	ds_write_b16_d16_hi v128, v78 offset:16112
	s_waitcnt lgkmcnt(0)
	s_barrier
	ds_read_b128 v[132:135], v129
	ds_read_b128 v[136:139], v129 offset:4352
	ds_read_b128 v[140:143], v129 offset:8704
	ds_read_b128 v[144:147], v129 offset:13056
	ds_read_b128 v[148:151], v129 offset:17408
	ds_read_b128 v[152:155], v129 offset:21760
	ds_read_b128 v[156:159], v129 offset:26112
	ds_read_b128 v[160:163], v129 offset:30464
	v_cvt_pk_bf16_f32 v48, v48, v49
	v_cvt_pk_bf16_f32 v50, v50, v51
	v_cvt_pk_bf16_f32 v52, v52, v53
	v_cvt_pk_bf16_f32 v54, v54, v55
	v_cvt_pk_bf16_f32 v56, v56, v57
	v_cvt_pk_bf16_f32 v58, v58, v59
	v_cvt_pk_bf16_f32 v60, v60, v61
	v_cvt_pk_bf16_f32 v62, v62, v63
	v_cvt_pk_bf16_f32 v32, v32, v33
	v_cvt_pk_bf16_f32 v34, v34, v35
	v_cvt_pk_bf16_f32 v36, v36, v37
	v_cvt_pk_bf16_f32 v38, v38, v39
	v_cvt_pk_bf16_f32 v40, v40, v41
	v_cvt_pk_bf16_f32 v42, v42, v43
	v_cvt_pk_bf16_f32 v44, v44, v45
	v_cvt_pk_bf16_f32 v46, v46, v47
	v_cvt_pk_bf16_f32 v16, v16, v17
	v_cvt_pk_bf16_f32 v18, v18, v19
	v_cvt_pk_bf16_f32 v20, v20, v21
	v_cvt_pk_bf16_f32 v22, v22, v23
	v_cvt_pk_bf16_f32 v24, v24, v25
	v_cvt_pk_bf16_f32 v26, v26, v27
	v_cvt_pk_bf16_f32 v28, v28, v29
	v_cvt_pk_bf16_f32 v30, v30, v31
	v_cvt_pk_bf16_f32 v0, v0, v1
	v_cvt_pk_bf16_f32 v2, v2, v3
	v_cvt_pk_bf16_f32 v4, v4, v5
	v_cvt_pk_bf16_f32 v6, v6, v7
	v_cvt_pk_bf16_f32 v8, v8, v9
	v_cvt_pk_bf16_f32 v10, v10, v11
	v_cvt_pk_bf16_f32 v12, v12, v13
	v_cvt_pk_bf16_f32 v14, v14, v15
	s_and_saveexec_b64 s[46:47], s[42:43]
	s_waitcnt lgkmcnt(7)
	global_store_dwordx4 v164, v[132:135], s[40:41]
	s_waitcnt lgkmcnt(6)
	global_store_dwordx4 v165, v[136:139], s[40:41]
	s_waitcnt lgkmcnt(5)
	global_store_dwordx4 v166, v[140:143], s[40:41]
	s_waitcnt lgkmcnt(4)
	global_store_dwordx4 v167, v[144:147], s[40:41]
	s_waitcnt lgkmcnt(3)
	global_store_dwordx4 v168, v[148:151], s[40:41]
	s_waitcnt lgkmcnt(2)
	global_store_dwordx4 v169, v[152:155], s[40:41]
	s_waitcnt lgkmcnt(1)
	global_store_dwordx4 v170, v[156:159], s[40:41]
	s_waitcnt lgkmcnt(0)
	global_store_dwordx4 v171, v[160:163], s[40:41]
	s_or_b64 exec, exec, s[46:47]
	s_barrier
	ds_write_b16 v128, v48
	ds_write_b16_d16_hi v128, v48 offset:272
	ds_write_b16 v128, v50 offset:544
	ds_write_b16_d16_hi v128, v50 offset:816
	ds_write_b16 v128, v52 offset:2176
	ds_write_b16_d16_hi v128, v52 offset:2448
	ds_write_b16 v128, v54 offset:2720
	ds_write_b16_d16_hi v128, v54 offset:2992
	ds_write_b16 v128, v56 offset:4352
	ds_write_b16_d16_hi v128, v56 offset:4624
	ds_write_b16 v128, v58 offset:4896
	ds_write_b16_d16_hi v128, v58 offset:5168
	ds_write_b16 v128, v60 offset:6528
	ds_write_b16_d16_hi v128, v60 offset:6800
	ds_write_b16 v128, v62 offset:7072
	ds_write_b16_d16_hi v128, v62 offset:7344
	ds_write_b16 v128, v32 offset:64
	ds_write_b16_d16_hi v128, v32 offset:336
	ds_write_b16 v128, v34 offset:608
	ds_write_b16_d16_hi v128, v34 offset:880
	ds_write_b16 v128, v36 offset:2240
	ds_write_b16_d16_hi v128, v36 offset:2512
	ds_write_b16 v128, v38 offset:2784
	ds_write_b16_d16_hi v128, v38 offset:3056
	ds_write_b16 v128, v40 offset:4416
	ds_write_b16_d16_hi v128, v40 offset:4688
	ds_write_b16 v128, v42 offset:4960
	ds_write_b16_d16_hi v128, v42 offset:5232
	ds_write_b16 v128, v44 offset:6592
	ds_write_b16_d16_hi v128, v44 offset:6864
	ds_write_b16 v128, v46 offset:7136
	ds_write_b16_d16_hi v128, v46 offset:7408
	ds_write_b16 v128, v16 offset:8704
	ds_write_b16_d16_hi v128, v16 offset:8976
	ds_write_b16 v128, v18 offset:9248
	ds_write_b16_d16_hi v128, v18 offset:9520
	ds_write_b16 v128, v20 offset:10880
	ds_write_b16_d16_hi v128, v20 offset:11152
	ds_write_b16 v128, v22 offset:11424
	ds_write_b16_d16_hi v128, v22 offset:11696
	ds_write_b16 v128, v24 offset:13056
	ds_write_b16_d16_hi v128, v24 offset:13328
	ds_write_b16 v128, v26 offset:13600
	ds_write_b16_d16_hi v128, v26 offset:13872
	ds_write_b16 v128, v28 offset:15232
	ds_write_b16_d16_hi v128, v28 offset:15504
	ds_write_b16 v128, v30 offset:15776
	ds_write_b16_d16_hi v128, v30 offset:16048
	ds_write_b16 v128, v0 offset:8768
	ds_write_b16_d16_hi v128, v0 offset:9040
	ds_write_b16 v128, v2 offset:9312
	ds_write_b16_d16_hi v128, v2 offset:9584
	ds_write_b16 v128, v4 offset:10944
	ds_write_b16_d16_hi v128, v4 offset:11216
	ds_write_b16 v128, v6 offset:11488
	ds_write_b16_d16_hi v128, v6 offset:11760
	ds_write_b16 v128, v8 offset:13120
	ds_write_b16_d16_hi v128, v8 offset:13392
	ds_write_b16 v128, v10 offset:13664
	ds_write_b16_d16_hi v128, v10 offset:13936
	ds_write_b16 v128, v12 offset:15296
	ds_write_b16_d16_hi v128, v12 offset:15568
	ds_write_b16 v128, v14 offset:15840
	ds_write_b16_d16_hi v128, v14 offset:16112
	s_waitcnt lgkmcnt(0)
	s_barrier
	ds_read_b128 v[132:135], v129
	ds_read_b128 v[136:139], v129 offset:4352
	ds_read_b128 v[140:143], v129 offset:8704
	ds_read_b128 v[144:147], v129 offset:13056
	ds_read_b128 v[148:151], v129 offset:17408
	ds_read_b128 v[152:155], v129 offset:21760
	ds_read_b128 v[156:159], v129 offset:26112
	ds_read_b128 v[160:163], v129 offset:30464
	v_add_u32_e32 v164, 0x49000, v164
	v_add_u32_e32 v165, 0x49000, v165
	v_add_u32_e32 v166, 0x49000, v166
	v_add_u32_e32 v167, 0x49000, v167
	v_add_u32_e32 v168, 0x49000, v168
	v_add_u32_e32 v169, 0x49000, v169
	v_add_u32_e32 v170, 0x49000, v170
	v_add_u32_e32 v171, 0x49000, v171
	s_and_saveexec_b64 s[46:47], s[42:43]
	s_waitcnt lgkmcnt(7)
	global_store_dwordx4 v164, v[132:135], s[40:41]
	s_waitcnt lgkmcnt(6)
	global_store_dwordx4 v165, v[136:139], s[40:41]
	s_waitcnt lgkmcnt(5)
	global_store_dwordx4 v166, v[140:143], s[40:41]
	s_waitcnt lgkmcnt(4)
	global_store_dwordx4 v167, v[144:147], s[40:41]
	s_waitcnt lgkmcnt(3)
	global_store_dwordx4 v168, v[148:151], s[40:41]
	s_waitcnt lgkmcnt(2)
	global_store_dwordx4 v169, v[152:155], s[40:41]
	s_waitcnt lgkmcnt(1)
	global_store_dwordx4 v170, v[156:159], s[40:41]
	s_waitcnt lgkmcnt(0)
	global_store_dwordx4 v171, v[160:163], s[40:41]
	s_or_b64 exec, exec, s[46:47]
	s_branch .Lmt4_tail_0

.LBB0_994:
	s_mov_b32 s43, 0
	s_and_b64 vcc, exec, s[4:5]
	s_mov_b32 s56, s19
	s_mov_b32 s57, s19
	s_cbranch_vccz .LBB0_996
	s_branch .LBB0_989
.LBB0_996:
	s_and_b32 s6, s56, 7
	s_and_b32 s10, s57, 7
	s_lshl_b32 s6, s6, 7
	s_or_b32 s62, s10, s18
	s_mov_b64 s[10:11], s[30:31]
	v_mov_b32_e32 v0, v177
	s_add_i32 s6, s23, s6
	s_lshl_b32 s59, s6, 11
	s_lshr_b32 s6, s57, 3
	v_mbcnt_lo_u32_b32 v0, -1, v0
	s_add_i32 s6, s21, s6
	v_mbcnt_hi_u32_b32 v0, -1, v0
	s_lshl_b32 s6, s6, 8
	v_add_u32_e32 v182, s33, v0
	s_lshl_b64 s[12:13], s[6:7], 11
	s_lshl_b32 s58, s62, 7
	s_add_u32 s60, s14, s12
	v_ashrrev_i32_e32 v0, 3, v182
	v_lshlrev_b32_e32 v183, 3, v182
	v_and_b32_e32 v6, 56, v183
	v_lshlrev_b32_e32 v1, 11, v0
	s_addc_u32 s61, s15, s13
	v_lshl_or_b32 v176, v6, 1, v1
	v_mul_lo_u32 v7, v0, s20
	v_lshl_add_u64 v[0:1], s[60:61], 0, v[176:177]
	v_add_co_u32_e32 v2, vcc, s24, v0
	s_lshl_b32 s62, s62, 18
	s_nop 0
	v_addc_co_u32_e32 v3, vcc, 0, v1, vcc
	v_add_co_u32_e32 v4, vcc, s25, v0
	s_add_u32 s62, s16, s62
	s_nop 0
	v_addc_co_u32_e32 v5, vcc, 0, v1, vcc
	global_load_dwordx4 v[128:131], v[2:3], off
	global_load_dwordx4 v[132:135], v[4:5], off
	v_add_co_u32_e32 v2, vcc, s26, v0
	s_addc_u32 s63, s17, 0
	s_nop 0
	v_addc_co_u32_e32 v3, vcc, 0, v1, vcc
	v_add_co_u32_e32 v4, vcc, s27, v0
	v_bfe_u32 v184, v182, 6, 1
	s_nop 0
	v_addc_co_u32_e32 v5, vcc, 0, v1, vcc
	global_load_dwordx4 v[136:139], v[2:3], off
	global_load_dwordx4 v[140:143], v[4:5], off
	v_add_co_u32_e32 v2, vcc, s34, v0
	v_and_b32_e32 v185, 31, v182
	s_nop 0
	v_addc_co_u32_e32 v3, vcc, 0, v1, vcc
	v_add_co_u32_e32 v4, vcc, s35, v0
	v_bfe_u32 v186, v182, 5, 1
	s_nop 0
	v_addc_co_u32_e32 v5, vcc, 0, v1, vcc
	v_add_co_u32_e32 v0, vcc, s36, v0
	global_load_dwordx4 v[144:147], v[2:3], off
	global_load_dwordx4 v[148:151], v[4:5], off
	v_addc_co_u32_e32 v1, vcc, 0, v1, vcc
	v_lshl_add_u64 v[2:3], s[62:63], 0, v[176:177]
	v_add_co_u32_e32 v4, vcc, s24, v2
	global_load_dwordx4 v[160:163], v176, s[60:61]
	global_load_dwordx4 v[152:155], v176, s[62:63]
	v_addc_co_u32_e32 v5, vcc, 0, v3, vcc
	global_load_dwordx4 v[156:159], v[0:1], off
	global_load_dwordx4 v[164:167], v[4:5], off
	v_add_co_u32_e32 v0, vcc, s25, v2
	s_add_u32 s60, s30, s59
	s_nop 0
	v_addc_co_u32_e32 v1, vcc, 0, v3, vcc
	v_add_co_u32_e32 v2, vcc, s26, v2
	s_addc_u32 s61, s31, 0
	s_nop 0
	v_addc_co_u32_e32 v3, vcc, 0, v3, vcc
	global_load_dwordx4 v[168:171], v[0:1], off
	global_load_dwordx4 v[172:175], v[2:3], off
	v_and_b32_e32 v0, 0xfffff9f, v182
	v_lshl_or_b32 v2, v184, 6, v185
	v_mul_lo_u32 v3, v0, s37
	v_or_b32_e32 v0, 0x60, v182
	s_add_u32 s12, s30, s12
	v_lshlrev_b32_e32 v1, 4, v186
	v_mul_lo_u32 v4, v0, s37
	v_mul_u32_u24_e32 v2, 0x90, v2
	s_addc_u32 s13, s31, s13
	v_mov_b32_e32 v0, 0
	v_add_lshl_u32 v189, v7, v6, 1
	v_lshl_add_u64 v[178:179], s[60:61], 0, v[176:177]
	v_lshl_add_u64 v[180:181], s[12:13], 0, v[176:177]
	s_mov_b64 s[12:13], 0
	v_add_u32_e32 v187, v1, v3
	v_add_u32_e32 v176, v1, v4
	v_add_u32_e32 v188, v1, v2
	v_mov_b32_e32 v1, v0
	v_mov_b32_e32 v2, v0
	v_mov_b32_e32 v3, v0
	v_mov_b32_e32 v4, v0
	v_mov_b32_e32 v5, v0
	v_mov_b32_e32 v6, v0
	v_mov_b32_e32 v7, v0
	v_mov_b32_e32 v8, v0
	v_mov_b32_e32 v9, v0
	v_mov_b32_e32 v10, v0
	v_mov_b32_e32 v11, v0
	v_mov_b32_e32 v12, v0
	v_mov_b32_e32 v13, v0
	v_mov_b32_e32 v14, v0
	v_mov_b32_e32 v15, v0
	v_mov_b32_e32 v16, v0
	v_mov_b32_e32 v17, v0
	v_mov_b32_e32 v18, v0
	v_mov_b32_e32 v19, v0
	v_mov_b32_e32 v20, v0
	v_mov_b32_e32 v21, v0
	v_mov_b32_e32 v22, v0
	v_mov_b32_e32 v23, v0
	v_mov_b32_e32 v24, v0
	v_mov_b32_e32 v25, v0
	v_mov_b32_e32 v26, v0
	v_mov_b32_e32 v27, v0
	v_mov_b32_e32 v28, v0
	v_mov_b32_e32 v29, v0
	v_mov_b32_e32 v30, v0
	v_mov_b32_e32 v31, v0
	v_mov_b32_e32 v32, v0
	v_mov_b32_e32 v33, v0
	v_mov_b32_e32 v34, v0
	v_mov_b32_e32 v35, v0
	v_mov_b32_e32 v36, v0
	v_mov_b32_e32 v37, v0
	v_mov_b32_e32 v38, v0
	v_mov_b32_e32 v39, v0
	v_mov_b32_e32 v40, v0
	v_mov_b32_e32 v41, v0
	v_mov_b32_e32 v42, v0
	v_mov_b32_e32 v43, v0
	v_mov_b32_e32 v44, v0
	v_mov_b32_e32 v45, v0
	v_mov_b32_e32 v46, v0
	v_mov_b32_e32 v47, v0
	v_mov_b32_e32 v48, v0
	v_mov_b32_e32 v49, v0
	v_mov_b32_e32 v50, v0
	v_mov_b32_e32 v51, v0
	v_mov_b32_e32 v52, v0
	v_mov_b32_e32 v53, v0
	v_mov_b32_e32 v54, v0
	v_mov_b32_e32 v55, v0
	v_mov_b32_e32 v56, v0
	v_mov_b32_e32 v57, v0
	v_mov_b32_e32 v58, v0
	v_mov_b32_e32 v59, v0
	v_mov_b32_e32 v60, v0
	v_mov_b32_e32 v61, v0
	v_mov_b32_e32 v62, v0
	v_mov_b32_e32 v63, v0
	v_mov_b32_e32 v64, v0
	v_mov_b32_e32 v65, v0
	v_mov_b32_e32 v66, v0
	v_mov_b32_e32 v67, v0
	v_mov_b32_e32 v68, v0
	v_mov_b32_e32 v69, v0
	v_mov_b32_e32 v70, v0
	v_mov_b32_e32 v71, v0
	v_mov_b32_e32 v72, v0
	v_mov_b32_e32 v73, v0
	v_mov_b32_e32 v74, v0
	v_mov_b32_e32 v75, v0
	v_mov_b32_e32 v76, v0
	v_mov_b32_e32 v77, v0
	v_mov_b32_e32 v78, v0
	v_mov_b32_e32 v79, v0
	v_mov_b32_e32 v80, v0
	v_mov_b32_e32 v81, v0
	v_mov_b32_e32 v82, v0
	v_mov_b32_e32 v83, v0
	v_mov_b32_e32 v84, v0
	v_mov_b32_e32 v85, v0
	v_mov_b32_e32 v86, v0
	v_mov_b32_e32 v87, v0
	v_mov_b32_e32 v88, v0
	v_mov_b32_e32 v89, v0
	v_mov_b32_e32 v90, v0
	v_mov_b32_e32 v91, v0
	v_mov_b32_e32 v92, v0
	v_mov_b32_e32 v93, v0
	v_mov_b32_e32 v94, v0
	v_mov_b32_e32 v95, v0
	v_mov_b32_e32 v96, v0
	v_mov_b32_e32 v97, v0
	v_mov_b32_e32 v98, v0
	v_mov_b32_e32 v99, v0
	v_mov_b32_e32 v100, v0
	v_mov_b32_e32 v101, v0
	v_mov_b32_e32 v102, v0
	v_mov_b32_e32 v103, v0
	v_mov_b32_e32 v104, v0
	v_mov_b32_e32 v105, v0
	v_mov_b32_e32 v106, v0
	v_mov_b32_e32 v107, v0
	v_mov_b32_e32 v108, v0
	v_mov_b32_e32 v109, v0
	v_mov_b32_e32 v110, v0
	v_mov_b32_e32 v111, v0
	v_mov_b32_e32 v112, v0
	v_mov_b32_e32 v113, v0
	v_mov_b32_e32 v114, v0
	v_mov_b32_e32 v115, v0
	v_mov_b32_e32 v116, v0
	v_mov_b32_e32 v117, v0
	v_mov_b32_e32 v118, v0
	v_mov_b32_e32 v119, v0
	v_mov_b32_e32 v120, v0
	v_mov_b32_e32 v121, v0
	v_mov_b32_e32 v122, v0
	v_mov_b32_e32 v123, v0
	v_mov_b32_e32 v124, v0
	v_mov_b32_e32 v125, v0
	v_mov_b32_e32 v126, v0
	v_mov_b32_e32 v127, v0
	s_cmp_eq_u32 s43, 0
	s_cbranch_scc1 .Lv5_a_1
	v_and_b32_e32 v3, 15, v182
	v_lshrrev_b32_e32 v4, 4, v182
	v_mul_u32_u24_e32 v2, 0x2000, v4
	v_lshl_add_u32 v2, v3, 4, v2
	v_mul_u32_u24_e32 v1, 0x110, v4
	v_lshl_add_u32 v1, v3, 4, v1
	v_lshrrev_b32_e32 v3, 7, v182
	v_bfe_u32 v4, v182, 5, 1
	v_lshlrev_b32_e32 v3, 6, v3
	v_lshl_or_b32 v3, v4, 2, v3
	v_mul_u32_u24_e32 v3, 136, v3
	v_and_b32_e32 v4, 0x5f, v182
	v_add_lshl_u32 v0, v3, v4, 1
	s_barrier
	ds_write_b16 v0, v190
	ds_write_b16_d16_hi v0, v190 offset:272
	ds_write_b16 v0, v191 offset:544
	ds_write_b16_d16_hi v0, v191 offset:816
	ds_write_b16 v0, v192 offset:2176
	ds_write_b16_d16_hi v0, v192 offset:2448
	ds_write_b16 v0, v193 offset:2720
	ds_write_b16_d16_hi v0, v193 offset:2992
	ds_write_b16 v0, v194 offset:4352
	ds_write_b16_d16_hi v0, v194 offset:4624
	ds_write_b16 v0, v195 offset:4896
	ds_write_b16_d16_hi v0, v195 offset:5168
	ds_write_b16 v0, v196 offset:6528
	ds_write_b16_d16_hi v0, v196 offset:6800
	ds_write_b16 v0, v197 offset:7072
	ds_write_b16_d16_hi v0, v197 offset:7344
	ds_write_b16 v0, v198 offset:64
	ds_write_b16_d16_hi v0, v198 offset:336
	ds_write_b16 v0, v199 offset:608
	ds_write_b16_d16_hi v0, v199 offset:880
	ds_write_b16 v0, v200 offset:2240
	ds_write_b16_d16_hi v0, v200 offset:2512
	ds_write_b16 v0, v201 offset:2784
	ds_write_b16_d16_hi v0, v201 offset:3056
	ds_write_b16 v0, v202 offset:4416
	ds_write_b16_d16_hi v0, v202 offset:4688
	ds_write_b16 v0, v203 offset:4960
	ds_write_b16_d16_hi v0, v203 offset:5232
	ds_write_b16 v0, v204 offset:6592
	ds_write_b16_d16_hi v0, v204 offset:6864
	ds_write_b16 v0, v205 offset:7136
	ds_write_b16_d16_hi v0, v205 offset:7408
	ds_write_b16 v0, v206 offset:8704
	ds_write_b16_d16_hi v0, v206 offset:8976
	ds_write_b16 v0, v207 offset:9248
	ds_write_b16_d16_hi v0, v207 offset:9520
	ds_write_b16 v0, v208 offset:10880
	ds_write_b16_d16_hi v0, v208 offset:11152
	ds_write_b16 v0, v209 offset:11424
	ds_write_b16_d16_hi v0, v209 offset:11696
	ds_write_b16 v0, v210 offset:13056
	ds_write_b16_d16_hi v0, v210 offset:13328
	ds_write_b16 v0, v211 offset:13600
	ds_write_b16_d16_hi v0, v211 offset:13872
	ds_write_b16 v0, v212 offset:15232
	ds_write_b16_d16_hi v0, v212 offset:15504
	ds_write_b16 v0, v213 offset:15776
	ds_write_b16_d16_hi v0, v213 offset:16048
	ds_write_b16 v0, v214 offset:8768
	ds_write_b16_d16_hi v0, v214 offset:9040
	ds_write_b16 v0, v215 offset:9312
	ds_write_b16_d16_hi v0, v215 offset:9584
	ds_write_b16 v0, v216 offset:10944
	ds_write_b16_d16_hi v0, v216 offset:11216
	ds_write_b16 v0, v217 offset:11488
	ds_write_b16_d16_hi v0, v217 offset:11760
	ds_write_b16 v0, v218 offset:13120
	ds_write_b16_d16_hi v0, v218 offset:13392
	ds_write_b16 v0, v219 offset:13664
	ds_write_b16_d16_hi v0, v219 offset:13936
	ds_write_b16 v0, v220 offset:15296
	ds_write_b16_d16_hi v0, v220 offset:15568
	ds_write_b16 v0, v221 offset:15840
	ds_write_b16_d16_hi v0, v221 offset:16112
	s_waitcnt lgkmcnt(0)
	s_barrier
	ds_read_b128 v[8:11], v1
	ds_read_b128 v[12:15], v1 offset:4352
	ds_read_b128 v[16:19], v1 offset:8704
	ds_read_b128 v[20:23], v1 offset:13056
	ds_read_b128 v[24:27], v1 offset:17408
	ds_read_b128 v[28:31], v1 offset:21760
	ds_read_b128 v[32:35], v1 offset:26112
	ds_read_b128 v[36:39], v1 offset:30464
	s_add_u32 s38, s44, 0x0
	s_addc_u32 s39, s45, 0
	s_waitcnt lgkmcnt(7)
	global_store_dwordx4 v2, v[8:11], s[38:39]
	s_add_u32 s38, s44, 0x20000
	s_addc_u32 s39, s45, 0
	s_waitcnt lgkmcnt(6)
	global_store_dwordx4 v2, v[12:15], s[38:39]
	s_add_u32 s38, s44, 0x40000
	s_addc_u32 s39, s45, 0
	s_waitcnt lgkmcnt(5)
	global_store_dwordx4 v2, v[16:19], s[38:39]
	s_add_u32 s38, s44, 0x60000
	s_addc_u32 s39, s45, 0
	s_waitcnt lgkmcnt(4)
	global_store_dwordx4 v2, v[20:23], s[38:39]
	s_add_u32 s38, s44, 0x100000
	s_addc_u32 s39, s45, 0
	s_waitcnt lgkmcnt(3)
	global_store_dwordx4 v2, v[24:27], s[38:39]
	s_add_u32 s38, s44, 0x120000
	s_addc_u32 s39, s45, 0
	s_waitcnt lgkmcnt(2)
	global_store_dwordx4 v2, v[28:31], s[38:39]
	s_add_u32 s38, s44, 0x140000
	s_addc_u32 s39, s45, 0
	s_waitcnt lgkmcnt(1)
	global_store_dwordx4 v2, v[32:35], s[38:39]
	s_add_u32 s38, s44, 0x160000
	s_addc_u32 s39, s45, 0
	s_waitcnt lgkmcnt(0)
	global_store_dwordx4 v2, v[36:39], s[38:39]
	s_barrier
	ds_write_b16 v0, v222
	ds_write_b16_d16_hi v0, v222 offset:272
	ds_write_b16 v0, v223 offset:544
	ds_write_b16_d16_hi v0, v223 offset:816
	ds_write_b16 v0, v224 offset:2176
	ds_write_b16_d16_hi v0, v224 offset:2448
	ds_write_b16 v0, v225 offset:2720
	ds_write_b16_d16_hi v0, v225 offset:2992
	ds_write_b16 v0, v226 offset:4352
	ds_write_b16_d16_hi v0, v226 offset:4624
	ds_write_b16 v0, v227 offset:4896
	ds_write_b16_d16_hi v0, v227 offset:5168
	ds_write_b16 v0, v228 offset:6528
	ds_write_b16_d16_hi v0, v228 offset:6800
	ds_write_b16 v0, v229 offset:7072
	ds_write_b16_d16_hi v0, v229 offset:7344
	ds_write_b16 v0, v230 offset:64
	ds_write_b16_d16_hi v0, v230 offset:336
	ds_write_b16 v0, v231 offset:608
	ds_write_b16_d16_hi v0, v231 offset:880
	ds_write_b16 v0, v232 offset:2240
	ds_write_b16_d16_hi v0, v232 offset:2512
	ds_write_b16 v0, v233 offset:2784
	ds_write_b16_d16_hi v0, v233 offset:3056
	ds_write_b16 v0, v234 offset:4416
	ds_write_b16_d16_hi v0, v234 offset:4688
	ds_write_b16 v0, v235 offset:4960
	ds_write_b16_d16_hi v0, v235 offset:5232
	ds_write_b16 v0, v236 offset:6592
	ds_write_b16_d16_hi v0, v236 offset:6864
	ds_write_b16 v0, v237 offset:7136
	ds_write_b16_d16_hi v0, v237 offset:7408
	ds_write_b16 v0, v238 offset:8704
	ds_write_b16_d16_hi v0, v238 offset:8976
	ds_write_b16 v0, v239 offset:9248
	ds_write_b16_d16_hi v0, v239 offset:9520
	ds_write_b16 v0, v240 offset:10880
	ds_write_b16_d16_hi v0, v240 offset:11152
	ds_write_b16 v0, v241 offset:11424
	ds_write_b16_d16_hi v0, v241 offset:11696
	ds_write_b16 v0, v242 offset:13056
	ds_write_b16_d16_hi v0, v242 offset:13328
	ds_write_b16 v0, v243 offset:13600
	ds_write_b16_d16_hi v0, v243 offset:13872
	ds_write_b16 v0, v244 offset:15232
	ds_write_b16_d16_hi v0, v244 offset:15504
	ds_write_b16 v0, v245 offset:15776
	ds_write_b16_d16_hi v0, v245 offset:16048
	ds_write_b16 v0, v246 offset:8768
	ds_write_b16_d16_hi v0, v246 offset:9040
	ds_write_b16 v0, v247 offset:9312
	ds_write_b16_d16_hi v0, v247 offset:9584
	ds_write_b16 v0, v248 offset:10944
	ds_write_b16_d16_hi v0, v248 offset:11216
	ds_write_b16 v0, v249 offset:11488
	ds_write_b16_d16_hi v0, v249 offset:11760
	ds_write_b16 v0, v250 offset:13120
	ds_write_b16_d16_hi v0, v250 offset:13392
	ds_write_b16 v0, v251 offset:13664
	ds_write_b16_d16_hi v0, v251 offset:13936
	ds_write_b16 v0, v252 offset:15296
	ds_write_b16_d16_hi v0, v252 offset:15568
	ds_write_b16 v0, v253 offset:15840
	ds_write_b16_d16_hi v0, v253 offset:16112
	s_waitcnt lgkmcnt(0)
	s_barrier
	ds_read_b128 v[8:11], v1
	ds_read_b128 v[12:15], v1 offset:4352
	ds_read_b128 v[16:19], v1 offset:8704
	ds_read_b128 v[20:23], v1 offset:13056
	ds_read_b128 v[24:27], v1 offset:17408
	ds_read_b128 v[28:31], v1 offset:21760
	ds_read_b128 v[32:35], v1 offset:26112
	ds_read_b128 v[36:39], v1 offset:30464
	s_add_u32 s38, s44, 0x80000
	s_addc_u32 s39, s45, 0
	s_waitcnt lgkmcnt(7)
	global_store_dwordx4 v2, v[8:11], s[38:39]
	s_add_u32 s38, s44, 0xa0000
	s_addc_u32 s39, s45, 0
	s_waitcnt lgkmcnt(6)
	global_store_dwordx4 v2, v[12:15], s[38:39]
	s_add_u32 s38, s44, 0xc0000
	s_addc_u32 s39, s45, 0
	s_waitcnt lgkmcnt(5)
	global_store_dwordx4 v2, v[16:19], s[38:39]
	s_add_u32 s38, s44, 0xe0000
	s_addc_u32 s39, s45, 0
	s_waitcnt lgkmcnt(4)
	global_store_dwordx4 v2, v[20:23], s[38:39]
	s_add_u32 s38, s44, 0x180000
	s_addc_u32 s39, s45, 0
	s_waitcnt lgkmcnt(3)
	global_store_dwordx4 v2, v[24:27], s[38:39]
	s_add_u32 s38, s44, 0x1a0000
	s_addc_u32 s39, s45, 0
	s_waitcnt lgkmcnt(2)
	global_store_dwordx4 v2, v[28:31], s[38:39]
	s_add_u32 s38, s44, 0x1c0000
	s_addc_u32 s39, s45, 0
	s_waitcnt lgkmcnt(1)
	global_store_dwordx4 v2, v[32:35], s[38:39]
	s_add_u32 s38, s44, 0x1e0000
	s_addc_u32 s39, s45, 0
	s_waitcnt lgkmcnt(0)
	global_store_dwordx4 v2, v[36:39], s[38:39]
	v_mov_b32_e32 v0, 0
	v_mov_b32_e32 v1, 0
	v_mov_b32_e32 v2, 0
	v_mov_b32_e32 v3, 0
	v_mov_b32_e32 v4, 0
	v_mov_b32_e32 v5, 0
	v_mov_b32_e32 v6, 0
	v_mov_b32_e32 v7, 0
	v_mov_b32_e32 v8, 0
	v_mov_b32_e32 v9, 0
	v_mov_b32_e32 v10, 0
	v_mov_b32_e32 v11, 0
	v_mov_b32_e32 v12, 0
	v_mov_b32_e32 v13, 0
	v_mov_b32_e32 v14, 0
	v_mov_b32_e32 v15, 0
	v_mov_b32_e32 v16, 0
	v_mov_b32_e32 v17, 0
	v_mov_b32_e32 v18, 0
	v_mov_b32_e32 v19, 0
	v_mov_b32_e32 v20, 0
	v_mov_b32_e32 v21, 0
	v_mov_b32_e32 v22, 0
	v_mov_b32_e32 v23, 0
	v_mov_b32_e32 v24, 0
	v_mov_b32_e32 v25, 0
	v_mov_b32_e32 v26, 0
	v_mov_b32_e32 v27, 0
	v_mov_b32_e32 v28, 0
	v_mov_b32_e32 v29, 0
	v_mov_b32_e32 v30, 0
	v_mov_b32_e32 v31, 0
	v_mov_b32_e32 v32, 0
	v_mov_b32_e32 v33, 0
	v_mov_b32_e32 v34, 0
	v_mov_b32_e32 v35, 0
	v_mov_b32_e32 v36, 0
	v_mov_b32_e32 v37, 0
	v_mov_b32_e32 v38, 0
	v_mov_b32_e32 v39, 0
.Lv5_a_1:
	v_readfirstlane_b32 s38, v180
	v_readfirstlane_b32 s39, v181
	v_readfirstlane_b32 s40, v178
	v_readfirstlane_b32 s41, v179
	v_lshrrev_b32_e32 v198, 3, v182
	v_and_b32_e32 v199, 7, v182
	v_lshlrev_b32_e32 v198, 11, v198
	v_lshl_or_b32 v190, v199, 4, v198
	s_lshl_b32 s42, s33, 8
	s_sub_u32 s38, s38, s42
	s_subb_u32 s39, s39, 0
	s_sub_u32 s40, s40, s42
	s_subb_u32 s41, s41, 0
	s_add_u32 s38, s38, 0x2957980
	s_addc_u32 s39, s39, 0
	s_add_u32 s40, s40, 0x6c0080
	s_addc_u32 s41, s41, 0
	v_add_u32_e32 v191, 0x10000, v190
	v_add_u32_e32 v192, 0x20000, v190
	v_add_u32_e32 v193, 0x30000, v190
	v_add_u32_e32 v194, 0x40000, v190
	v_add_u32_e32 v195, 0x50000, v190
	v_add_u32_e32 v196, 0x60000, v190
	v_add_u32_e32 v197, 0x70000, v190
	s_waitcnt lgkmcnt(0)
	s_barrier
	s_cmp_eq_u32 s43, 0
	s_cbranch_scc1 .Lv5_b_1
	s_waitcnt vmcnt(16)
	s_mov_b32 s43, 0
	s_branch .Lv5_c_1
.Lv5_b_1:
	s_waitcnt vmcnt(0)
.Lv5_c_1:
	ds_write_b128 v189, v[160:163]
	ds_write_b128 v189, v[128:131] offset:4608
	ds_write_b128 v189, v[132:135] offset:9216
	ds_write_b128 v189, v[136:139] offset:13824
	ds_write_b128 v189, v[140:143] offset:18432
	ds_write_b128 v189, v[144:147] offset:23040
	ds_write_b128 v189, v[148:151] offset:27648
	ds_write_b128 v189, v[156:159] offset:32256
	ds_write_b128 v189, v[152:155] offset:36864
	ds_write_b128 v189, v[164:167] offset:41472
	ds_write_b128 v189, v[168:171] offset:46080
	ds_write_b128 v189, v[172:175] offset:50688
	s_waitcnt lgkmcnt(0)
	s_barrier
.LBB0_997:
	ds_read_b128 v[216:219], v188 offset:36864
	ds_read_b128 v[200:203], v187
	ds_read_b128 v[220:223], v188 offset:41472
	ds_read_b128 v[204:207], v187 offset:4608
	ds_read_b128 v[208:211], v187 offset:9216
	ds_read_b128 v[212:215], v176
	s_waitcnt lgkmcnt(4)
	v_mfma_f32_32x32x16_bf16 v[112:127], v[200:203], v[216:219], v[112:127]
	ds_read_b128 v[240:243], v188 offset:36896
	global_load_dwordx4 v[160:163], v190, s[38:39]
	s_waitcnt lgkmcnt(4)
	v_mfma_f32_32x32x16_bf16 v[96:111], v[200:203], v[220:223], v[96:111]
	ds_read_b128 v[224:227], v187 offset:32
	global_load_dwordx4 v[128:131], v191, s[38:39]
	s_waitcnt lgkmcnt(4)
	v_mfma_f32_32x32x16_bf16 v[80:95], v[204:207], v[216:219], v[80:95]
	ds_read_b128 v[244:247], v188 offset:41504
	global_load_dwordx4 v[132:135], v192, s[38:39]
	s_waitcnt lgkmcnt(5)
	v_mfma_f32_32x32x16_bf16 v[64:79], v[204:207], v[220:223], v[64:79]
	ds_read_b128 v[228:231], v187 offset:4640
	global_load_dwordx4 v[136:139], v193, s[38:39]
	s_waitcnt lgkmcnt(5)
	v_mfma_f32_32x32x16_bf16 v[48:63], v[208:211], v[216:219], v[48:63]
	ds_read_b128 v[232:235], v187 offset:9248
	global_load_dwordx4 v[140:143], v194, s[38:39]
	s_waitcnt lgkmcnt(6)
	v_mfma_f32_32x32x16_bf16 v[32:47], v[208:211], v[220:223], v[32:47]
	ds_read_b128 v[236:239], v176 offset:32
	global_load_dwordx4 v[144:147], v195, s[38:39]
	s_waitcnt lgkmcnt(6)
	v_mfma_f32_32x32x16_bf16 v[16:31], v[212:215], v[216:219], v[16:31]
	global_load_dwordx4 v[148:151], v196, s[38:39]
	global_load_dwordx4 v[156:159], v197, s[38:39]
	s_waitcnt lgkmcnt(6)
	v_mfma_f32_32x32x16_bf16 v[0:15], v[212:215], v[220:223], v[0:15]
	global_load_dwordx4 v[152:155], v190, s[40:41]
	global_load_dwordx4 v[164:167], v191, s[40:41]
	s_waitcnt lgkmcnt(4)
	v_mfma_f32_32x32x16_bf16 v[112:127], v[224:227], v[240:243], v[112:127]
	ds_read_b128 v[200:203], v187 offset:64
	global_load_dwordx4 v[168:171], v192, s[40:41]
	s_waitcnt lgkmcnt(4)
	v_mfma_f32_32x32x16_bf16 v[96:111], v[224:227], v[244:247], v[96:111]
	ds_read_b128 v[204:207], v187 offset:4672
	global_load_dwordx4 v[172:175], v193, s[40:41]
	s_add_u32 s38, s38, 0x80
	s_addc_u32 s39, s39, 0
	s_add_u32 s40, s40, 0x80
	s_addc_u32 s41, s41, 0
	s_add_u32 s12, s12, 0x80
	s_waitcnt lgkmcnt(4)
	v_mfma_f32_32x32x16_bf16 v[80:95], v[228:231], v[240:243], v[80:95]
	ds_read_b128 v[208:211], v187 offset:9280
	s_waitcnt lgkmcnt(5)
	v_mfma_f32_32x32x16_bf16 v[64:79], v[228:231], v[244:247], v[64:79]
	ds_read_b128 v[212:215], v176 offset:64
	s_waitcnt lgkmcnt(5)
	v_mfma_f32_32x32x16_bf16 v[48:63], v[232:235], v[240:243], v[48:63]
	ds_read_b128 v[216:219], v188 offset:36928
	s_waitcnt lgkmcnt(6)
	v_mfma_f32_32x32x16_bf16 v[32:47], v[232:235], v[244:247], v[32:47]
	ds_read_b128 v[220:223], v188 offset:41536
	s_waitcnt lgkmcnt(6)
	v_mfma_f32_32x32x16_bf16 v[16:31], v[236:239], v[240:243], v[16:31]
	s_waitcnt lgkmcnt(6)
	v_mfma_f32_32x32x16_bf16 v[0:15], v[236:239], v[244:247], v[0:15]
	s_waitcnt lgkmcnt(1)
	v_mfma_f32_32x32x16_bf16 v[112:127], v[200:203], v[216:219], v[112:127]
	ds_read_b128 v[224:227], v187 offset:96
	s_waitcnt lgkmcnt(1)
	v_mfma_f32_32x32x16_bf16 v[96:111], v[200:203], v[220:223], v[96:111]
	ds_read_b128 v[228:231], v187 offset:4704
	s_waitcnt lgkmcnt(3)
	v_mfma_f32_32x32x16_bf16 v[80:95], v[204:207], v[216:219], v[80:95]
	ds_read_b128 v[232:235], v187 offset:9312
	s_waitcnt lgkmcnt(3)
	v_mfma_f32_32x32x16_bf16 v[64:79], v[204:207], v[220:223], v[64:79]
	ds_read_b128 v[236:239], v176 offset:96
	s_waitcnt lgkmcnt(5)
	v_mfma_f32_32x32x16_bf16 v[48:63], v[208:211], v[216:219], v[48:63]
	ds_read_b128 v[240:243], v188 offset:36960
	s_waitcnt lgkmcnt(5)
	v_mfma_f32_32x32x16_bf16 v[32:47], v[208:211], v[220:223], v[32:47]
	ds_read_b128 v[244:247], v188 offset:41568
	s_waitcnt lgkmcnt(7)
	v_mfma_f32_32x32x16_bf16 v[16:31], v[212:215], v[216:219], v[16:31]
	s_waitcnt lgkmcnt(6)
	v_mfma_f32_32x32x16_bf16 v[0:15], v[212:215], v[220:223], v[0:15]
	s_waitcnt lgkmcnt(0)
	s_barrier
	s_waitcnt vmcnt(0)
	s_waitcnt lgkmcnt(1)
	v_mfma_f32_32x32x16_bf16 v[112:127], v[224:227], v[240:243], v[112:127]
	ds_write_b128 v189, v[160:163]
	ds_write_b128 v189, v[128:131] offset:4608
	s_waitcnt lgkmcnt(2)
	v_mfma_f32_32x32x16_bf16 v[96:111], v[224:227], v[244:247], v[96:111]
	ds_write_b128 v189, v[132:135] offset:9216
	s_waitcnt lgkmcnt(4)
	v_mfma_f32_32x32x16_bf16 v[80:95], v[228:231], v[240:243], v[80:95]
	ds_write_b128 v189, v[136:139] offset:13824
	ds_write_b128 v189, v[140:143] offset:18432
	s_waitcnt lgkmcnt(5)
	v_mfma_f32_32x32x16_bf16 v[64:79], v[228:231], v[244:247], v[64:79]
	ds_write_b128 v189, v[144:147] offset:23040
	s_waitcnt lgkmcnt(7)
	v_mfma_f32_32x32x16_bf16 v[48:63], v[232:235], v[240:243], v[48:63]
	ds_write_b128 v189, v[148:151] offset:27648
	ds_write_b128 v189, v[156:159] offset:32256
	s_waitcnt lgkmcnt(8)
	v_mfma_f32_32x32x16_bf16 v[32:47], v[232:235], v[244:247], v[32:47]
	ds_write_b128 v189, v[152:155] offset:36864
	s_waitcnt lgkmcnt(10)
	v_mfma_f32_32x32x16_bf16 v[16:31], v[236:239], v[240:243], v[16:31]
	ds_write_b128 v189, v[164:167] offset:41472
	ds_write_b128 v189, v[168:171] offset:46080
	s_waitcnt lgkmcnt(11)
	v_mfma_f32_32x32x16_bf16 v[0:15], v[236:239], v[244:247], v[0:15]
	ds_write_b128 v189, v[172:175] offset:50688
	s_waitcnt lgkmcnt(0)
	s_barrier
	s_cmpk_lg_i32 s12, 0x780
	s_cbranch_scc1 .LBB0_997
	ds_read_b128 v[216:219], v188 offset:36864
	ds_read_b128 v[200:203], v187
	ds_read_b128 v[220:223], v188 offset:41472
	ds_read_b128 v[204:207], v187 offset:4608
	ds_read_b128 v[208:211], v187 offset:9216
	ds_read_b128 v[212:215], v176
	s_waitcnt lgkmcnt(4)
	v_mfma_f32_32x32x16_bf16 v[112:127], v[200:203], v[216:219], v[112:127]
	ds_read_b128 v[240:243], v188 offset:36896
	s_waitcnt lgkmcnt(4)
	v_mfma_f32_32x32x16_bf16 v[96:111], v[200:203], v[220:223], v[96:111]
	ds_read_b128 v[224:227], v187 offset:32
	s_waitcnt lgkmcnt(4)
	v_mfma_f32_32x32x16_bf16 v[80:95], v[204:207], v[216:219], v[80:95]
	ds_read_b128 v[244:247], v188 offset:41504
	s_waitcnt lgkmcnt(5)
	v_mfma_f32_32x32x16_bf16 v[64:79], v[204:207], v[220:223], v[64:79]
	ds_read_b128 v[228:231], v187 offset:4640
	s_waitcnt lgkmcnt(5)
	v_mfma_f32_32x32x16_bf16 v[48:63], v[208:211], v[216:219], v[48:63]
	ds_read_b128 v[232:235], v187 offset:9248
	s_waitcnt lgkmcnt(6)
	v_mfma_f32_32x32x16_bf16 v[32:47], v[208:211], v[220:223], v[32:47]
	ds_read_b128 v[236:239], v176 offset:32
	s_waitcnt lgkmcnt(6)
	v_mfma_f32_32x32x16_bf16 v[16:31], v[212:215], v[216:219], v[16:31]
	s_waitcnt lgkmcnt(6)
	v_mfma_f32_32x32x16_bf16 v[0:15], v[212:215], v[220:223], v[0:15]
	s_waitcnt lgkmcnt(4)
	v_mfma_f32_32x32x16_bf16 v[112:127], v[224:227], v[240:243], v[112:127]
	ds_read_b128 v[200:203], v187 offset:64
	s_waitcnt lgkmcnt(4)
	v_mfma_f32_32x32x16_bf16 v[96:111], v[224:227], v[244:247], v[96:111]
	ds_read_b128 v[204:207], v187 offset:4672
	s_waitcnt lgkmcnt(4)
	v_mfma_f32_32x32x16_bf16 v[80:95], v[228:231], v[240:243], v[80:95]
	ds_read_b128 v[208:211], v187 offset:9280
	s_waitcnt lgkmcnt(5)
	v_mfma_f32_32x32x16_bf16 v[64:79], v[228:231], v[244:247], v[64:79]
	ds_read_b128 v[212:215], v176 offset:64
	s_waitcnt lgkmcnt(5)
	v_mfma_f32_32x32x16_bf16 v[48:63], v[232:235], v[240:243], v[48:63]
	ds_read_b128 v[216:219], v188 offset:36928
	s_waitcnt lgkmcnt(6)
	v_mfma_f32_32x32x16_bf16 v[32:47], v[232:235], v[244:247], v[32:47]
	ds_read_b128 v[220:223], v188 offset:41536
	s_waitcnt lgkmcnt(6)
	v_mfma_f32_32x32x16_bf16 v[16:31], v[236:239], v[240:243], v[16:31]
	s_waitcnt lgkmcnt(6)
	v_mfma_f32_32x32x16_bf16 v[0:15], v[236:239], v[244:247], v[0:15]
	s_waitcnt lgkmcnt(1)
	v_mfma_f32_32x32x16_bf16 v[112:127], v[200:203], v[216:219], v[112:127]
	ds_read_b128 v[224:227], v187 offset:96
	s_waitcnt lgkmcnt(1)
	v_mfma_f32_32x32x16_bf16 v[96:111], v[200:203], v[220:223], v[96:111]
	ds_read_b128 v[228:231], v187 offset:4704
	s_waitcnt lgkmcnt(3)
	v_mfma_f32_32x32x16_bf16 v[80:95], v[204:207], v[216:219], v[80:95]
	ds_read_b128 v[232:235], v187 offset:9312
	s_waitcnt lgkmcnt(3)
	v_mfma_f32_32x32x16_bf16 v[64:79], v[204:207], v[220:223], v[64:79]
	ds_read_b128 v[236:239], v176 offset:96
	s_waitcnt lgkmcnt(5)
	v_mfma_f32_32x32x16_bf16 v[48:63], v[208:211], v[216:219], v[48:63]
	ds_read_b128 v[240:243], v188 offset:36960
	s_waitcnt lgkmcnt(5)
	v_mfma_f32_32x32x16_bf16 v[32:47], v[208:211], v[220:223], v[32:47]
	ds_read_b128 v[244:247], v188 offset:41568
	s_waitcnt lgkmcnt(7)
	v_mfma_f32_32x32x16_bf16 v[16:31], v[212:215], v[216:219], v[16:31]
	s_waitcnt lgkmcnt(6)
	v_mfma_f32_32x32x16_bf16 v[0:15], v[212:215], v[220:223], v[0:15]
	s_waitcnt lgkmcnt(1)
	v_mfma_f32_32x32x16_bf16 v[112:127], v[224:227], v[240:243], v[112:127]
	s_waitcnt lgkmcnt(0)
	v_mfma_f32_32x32x16_bf16 v[96:111], v[224:227], v[244:247], v[96:111]
	s_waitcnt lgkmcnt(1)
	v_mfma_f32_32x32x16_bf16 v[80:95], v[228:231], v[240:243], v[80:95]
	s_waitcnt lgkmcnt(0)
	v_mfma_f32_32x32x16_bf16 v[64:79], v[228:231], v[244:247], v[64:79]
	s_waitcnt lgkmcnt(1)
	v_mfma_f32_32x32x16_bf16 v[48:63], v[232:235], v[240:243], v[48:63]
	s_waitcnt lgkmcnt(0)
	v_mfma_f32_32x32x16_bf16 v[32:47], v[232:235], v[244:247], v[32:47]
	s_waitcnt lgkmcnt(1)
	v_mfma_f32_32x32x16_bf16 v[16:31], v[236:239], v[240:243], v[16:31]
	s_waitcnt lgkmcnt(0)
	v_mfma_f32_32x32x16_bf16 v[0:15], v[236:239], v[244:247], v[0:15]
	s_mul_i32 s42, s6, 0x2000
	s_add_u32 s44, s30, s42
	s_addc_u32 s45, s31, 0
	s_lshl_b32 s42, s58, 1
	s_add_u32 s44, s44, s42
	s_addc_u32 s45, s45, 0
	s_add_u32 s44, s44, 0x7157900
	s_addc_u32 s45, s45, 0
	s_mov_b32 s43, 1
	v_max_f32_e32 v112, 0, v112
	v_max_f32_e32 v113, 0, v113
	v_mul_f32_e32 v112, v112, v112
	v_mul_f32_e32 v113, v113, v113
	v_cvt_pk_bf16_f32 v190, v112, v113
	v_max_f32_e32 v114, 0, v114
	v_max_f32_e32 v115, 0, v115
	v_mul_f32_e32 v114, v114, v114
	v_mul_f32_e32 v115, v115, v115
	v_cvt_pk_bf16_f32 v191, v114, v115
	v_max_f32_e32 v116, 0, v116
	v_max_f32_e32 v117, 0, v117
	v_mul_f32_e32 v116, v116, v116
	v_mul_f32_e32 v117, v117, v117
	v_cvt_pk_bf16_f32 v192, v116, v117
	v_max_f32_e32 v118, 0, v118
	v_max_f32_e32 v119, 0, v119
	v_mul_f32_e32 v118, v118, v118
	v_mul_f32_e32 v119, v119, v119
	v_cvt_pk_bf16_f32 v193, v118, v119
	v_max_f32_e32 v120, 0, v120
	v_max_f32_e32 v121, 0, v121
	v_mul_f32_e32 v120, v120, v120
	v_mul_f32_e32 v121, v121, v121
	v_cvt_pk_bf16_f32 v194, v120, v121
	v_max_f32_e32 v122, 0, v122
	v_max_f32_e32 v123, 0, v123
	v_mul_f32_e32 v122, v122, v122
	v_mul_f32_e32 v123, v123, v123
	v_cvt_pk_bf16_f32 v195, v122, v123
	v_max_f32_e32 v124, 0, v124
	v_max_f32_e32 v125, 0, v125
	v_mul_f32_e32 v124, v124, v124
	v_mul_f32_e32 v125, v125, v125
	v_cvt_pk_bf16_f32 v196, v124, v125
	v_max_f32_e32 v126, 0, v126
	v_max_f32_e32 v127, 0, v127
	v_mul_f32_e32 v126, v126, v126
	v_mul_f32_e32 v127, v127, v127
	v_cvt_pk_bf16_f32 v197, v126, v127
	v_max_f32_e32 v96, 0, v96
	v_max_f32_e32 v97, 0, v97
	v_mul_f32_e32 v96, v96, v96
	v_mul_f32_e32 v97, v97, v97
	v_cvt_pk_bf16_f32 v198, v96, v97
	v_max_f32_e32 v98, 0, v98
	v_max_f32_e32 v99, 0, v99
	v_mul_f32_e32 v98, v98, v98
	v_mul_f32_e32 v99, v99, v99
	v_cvt_pk_bf16_f32 v199, v98, v99
	v_max_f32_e32 v100, 0, v100
	v_max_f32_e32 v101, 0, v101
	v_mul_f32_e32 v100, v100, v100
	v_mul_f32_e32 v101, v101, v101
	v_cvt_pk_bf16_f32 v200, v100, v101
	v_max_f32_e32 v102, 0, v102
	v_max_f32_e32 v103, 0, v103
	v_mul_f32_e32 v102, v102, v102
	v_mul_f32_e32 v103, v103, v103
	v_cvt_pk_bf16_f32 v201, v102, v103
	v_max_f32_e32 v104, 0, v104
	v_max_f32_e32 v105, 0, v105
	v_mul_f32_e32 v104, v104, v104
	v_mul_f32_e32 v105, v105, v105
	v_cvt_pk_bf16_f32 v202, v104, v105
	v_max_f32_e32 v106, 0, v106
	v_max_f32_e32 v107, 0, v107
	v_mul_f32_e32 v106, v106, v106
	v_mul_f32_e32 v107, v107, v107
	v_cvt_pk_bf16_f32 v203, v106, v107
	v_max_f32_e32 v108, 0, v108
	v_max_f32_e32 v109, 0, v109
	v_mul_f32_e32 v108, v108, v108
	v_mul_f32_e32 v109, v109, v109
	v_cvt_pk_bf16_f32 v204, v108, v109
	v_max_f32_e32 v110, 0, v110
	v_max_f32_e32 v111, 0, v111
	v_mul_f32_e32 v110, v110, v110
	v_mul_f32_e32 v111, v111, v111
	v_cvt_pk_bf16_f32 v205, v110, v111
	v_max_f32_e32 v80, 0, v80
	v_max_f32_e32 v81, 0, v81
	v_mul_f32_e32 v80, v80, v80
	v_mul_f32_e32 v81, v81, v81
	v_cvt_pk_bf16_f32 v206, v80, v81
	v_max_f32_e32 v82, 0, v82
	v_max_f32_e32 v83, 0, v83
	v_mul_f32_e32 v82, v82, v82
	v_mul_f32_e32 v83, v83, v83
	v_cvt_pk_bf16_f32 v207, v82, v83
	v_max_f32_e32 v84, 0, v84
	v_max_f32_e32 v85, 0, v85
	v_mul_f32_e32 v84, v84, v84
	v_mul_f32_e32 v85, v85, v85
	v_cvt_pk_bf16_f32 v208, v84, v85
	v_max_f32_e32 v86, 0, v86
	v_max_f32_e32 v87, 0, v87
	v_mul_f32_e32 v86, v86, v86
	v_mul_f32_e32 v87, v87, v87
	v_cvt_pk_bf16_f32 v209, v86, v87
	v_max_f32_e32 v88, 0, v88
	v_max_f32_e32 v89, 0, v89
	v_mul_f32_e32 v88, v88, v88
	v_mul_f32_e32 v89, v89, v89
	v_cvt_pk_bf16_f32 v210, v88, v89
	v_max_f32_e32 v90, 0, v90
	v_max_f32_e32 v91, 0, v91
	v_mul_f32_e32 v90, v90, v90
	v_mul_f32_e32 v91, v91, v91
	v_cvt_pk_bf16_f32 v211, v90, v91
	v_max_f32_e32 v92, 0, v92
	v_max_f32_e32 v93, 0, v93
	v_mul_f32_e32 v92, v92, v92
	v_mul_f32_e32 v93, v93, v93
	v_cvt_pk_bf16_f32 v212, v92, v93
	v_max_f32_e32 v94, 0, v94
	v_max_f32_e32 v95, 0, v95
	v_mul_f32_e32 v94, v94, v94
	v_mul_f32_e32 v95, v95, v95
	v_cvt_pk_bf16_f32 v213, v94, v95
	v_max_f32_e32 v64, 0, v64
	v_max_f32_e32 v65, 0, v65
	v_mul_f32_e32 v64, v64, v64
	v_mul_f32_e32 v65, v65, v65
	v_cvt_pk_bf16_f32 v214, v64, v65
	v_max_f32_e32 v66, 0, v66
	v_max_f32_e32 v67, 0, v67
	v_mul_f32_e32 v66, v66, v66
	v_mul_f32_e32 v67, v67, v67
	v_cvt_pk_bf16_f32 v215, v66, v67
	v_max_f32_e32 v68, 0, v68
	v_max_f32_e32 v69, 0, v69
	v_mul_f32_e32 v68, v68, v68
	v_mul_f32_e32 v69, v69, v69
	v_cvt_pk_bf16_f32 v216, v68, v69
	v_max_f32_e32 v70, 0, v70
	v_max_f32_e32 v71, 0, v71
	v_mul_f32_e32 v70, v70, v70
	v_mul_f32_e32 v71, v71, v71
	v_cvt_pk_bf16_f32 v217, v70, v71
	v_max_f32_e32 v72, 0, v72
	v_max_f32_e32 v73, 0, v73
	v_mul_f32_e32 v72, v72, v72
	v_mul_f32_e32 v73, v73, v73
	v_cvt_pk_bf16_f32 v218, v72, v73
	v_max_f32_e32 v74, 0, v74
	v_max_f32_e32 v75, 0, v75
	v_mul_f32_e32 v74, v74, v74
	v_mul_f32_e32 v75, v75, v75
	v_cvt_pk_bf16_f32 v219, v74, v75
	v_max_f32_e32 v76, 0, v76
	v_max_f32_e32 v77, 0, v77
	v_mul_f32_e32 v76, v76, v76
	v_mul_f32_e32 v77, v77, v77
	v_cvt_pk_bf16_f32 v220, v76, v77
	v_max_f32_e32 v78, 0, v78
	v_max_f32_e32 v79, 0, v79
	v_mul_f32_e32 v78, v78, v78
	v_mul_f32_e32 v79, v79, v79
	v_cvt_pk_bf16_f32 v221, v78, v79
	v_max_f32_e32 v48, 0, v48
	v_max_f32_e32 v49, 0, v49
	v_mul_f32_e32 v48, v48, v48
	v_mul_f32_e32 v49, v49, v49
	v_cvt_pk_bf16_f32 v222, v48, v49
	v_max_f32_e32 v50, 0, v50
	v_max_f32_e32 v51, 0, v51
	v_mul_f32_e32 v50, v50, v50
	v_mul_f32_e32 v51, v51, v51
	v_cvt_pk_bf16_f32 v223, v50, v51
	v_max_f32_e32 v52, 0, v52
	v_max_f32_e32 v53, 0, v53
	v_mul_f32_e32 v52, v52, v52
	v_mul_f32_e32 v53, v53, v53
	v_cvt_pk_bf16_f32 v224, v52, v53
	v_max_f32_e32 v54, 0, v54
	v_max_f32_e32 v55, 0, v55
	v_mul_f32_e32 v54, v54, v54
	v_mul_f32_e32 v55, v55, v55
	v_cvt_pk_bf16_f32 v225, v54, v55
	v_max_f32_e32 v56, 0, v56
	v_max_f32_e32 v57, 0, v57
	v_mul_f32_e32 v56, v56, v56
	v_mul_f32_e32 v57, v57, v57
	v_cvt_pk_bf16_f32 v226, v56, v57
	v_max_f32_e32 v58, 0, v58
	v_max_f32_e32 v59, 0, v59
	v_mul_f32_e32 v58, v58, v58
	v_mul_f32_e32 v59, v59, v59
	v_cvt_pk_bf16_f32 v227, v58, v59
	v_max_f32_e32 v60, 0, v60
	v_max_f32_e32 v61, 0, v61
	v_mul_f32_e32 v60, v60, v60
	v_mul_f32_e32 v61, v61, v61
	v_cvt_pk_bf16_f32 v228, v60, v61
	v_max_f32_e32 v62, 0, v62
	v_max_f32_e32 v63, 0, v63
	v_mul_f32_e32 v62, v62, v62
	v_mul_f32_e32 v63, v63, v63
	v_cvt_pk_bf16_f32 v229, v62, v63
	v_max_f32_e32 v32, 0, v32
	v_max_f32_e32 v33, 0, v33
	v_mul_f32_e32 v32, v32, v32
	v_mul_f32_e32 v33, v33, v33
	v_cvt_pk_bf16_f32 v230, v32, v33
	v_max_f32_e32 v34, 0, v34
	v_max_f32_e32 v35, 0, v35
	v_mul_f32_e32 v34, v34, v34
	v_mul_f32_e32 v35, v35, v35
	v_cvt_pk_bf16_f32 v231, v34, v35
	v_max_f32_e32 v36, 0, v36
	v_max_f32_e32 v37, 0, v37
	v_mul_f32_e32 v36, v36, v36
	v_mul_f32_e32 v37, v37, v37
	v_cvt_pk_bf16_f32 v232, v36, v37
	v_max_f32_e32 v38, 0, v38
	v_max_f32_e32 v39, 0, v39
	v_mul_f32_e32 v38, v38, v38
	v_mul_f32_e32 v39, v39, v39
	v_cvt_pk_bf16_f32 v233, v38, v39
	v_max_f32_e32 v40, 0, v40
	v_max_f32_e32 v41, 0, v41
	v_mul_f32_e32 v40, v40, v40
	v_mul_f32_e32 v41, v41, v41
	v_cvt_pk_bf16_f32 v234, v40, v41
	v_max_f32_e32 v42, 0, v42
	v_max_f32_e32 v43, 0, v43
	v_mul_f32_e32 v42, v42, v42
	v_mul_f32_e32 v43, v43, v43
	v_cvt_pk_bf16_f32 v235, v42, v43
	v_max_f32_e32 v44, 0, v44
	v_max_f32_e32 v45, 0, v45
	v_mul_f32_e32 v44, v44, v44
	v_mul_f32_e32 v45, v45, v45
	v_cvt_pk_bf16_f32 v236, v44, v45
	v_max_f32_e32 v46, 0, v46
	v_max_f32_e32 v47, 0, v47
	v_mul_f32_e32 v46, v46, v46
	v_mul_f32_e32 v47, v47, v47
	v_cvt_pk_bf16_f32 v237, v46, v47
	v_max_f32_e32 v16, 0, v16
	v_max_f32_e32 v17, 0, v17
	v_mul_f32_e32 v16, v16, v16
	v_mul_f32_e32 v17, v17, v17
	v_cvt_pk_bf16_f32 v238, v16, v17
	v_max_f32_e32 v18, 0, v18
	v_max_f32_e32 v19, 0, v19
	v_mul_f32_e32 v18, v18, v18
	v_mul_f32_e32 v19, v19, v19
	v_cvt_pk_bf16_f32 v239, v18, v19
	v_max_f32_e32 v20, 0, v20
	v_max_f32_e32 v21, 0, v21
	v_mul_f32_e32 v20, v20, v20
	v_mul_f32_e32 v21, v21, v21
	v_cvt_pk_bf16_f32 v240, v20, v21
	v_max_f32_e32 v22, 0, v22
	v_max_f32_e32 v23, 0, v23
	v_mul_f32_e32 v22, v22, v22
	v_mul_f32_e32 v23, v23, v23
	v_cvt_pk_bf16_f32 v241, v22, v23
	v_max_f32_e32 v24, 0, v24
	v_max_f32_e32 v25, 0, v25
	v_mul_f32_e32 v24, v24, v24
	v_mul_f32_e32 v25, v25, v25
	v_cvt_pk_bf16_f32 v242, v24, v25
	v_max_f32_e32 v26, 0, v26
	v_max_f32_e32 v27, 0, v27
	v_mul_f32_e32 v26, v26, v26
	v_mul_f32_e32 v27, v27, v27
	v_cvt_pk_bf16_f32 v243, v26, v27
	v_max_f32_e32 v28, 0, v28
	v_max_f32_e32 v29, 0, v29
	v_mul_f32_e32 v28, v28, v28
	v_mul_f32_e32 v29, v29, v29
	v_cvt_pk_bf16_f32 v244, v28, v29
	v_max_f32_e32 v30, 0, v30
	v_max_f32_e32 v31, 0, v31
	v_mul_f32_e32 v30, v30, v30
	v_mul_f32_e32 v31, v31, v31
	v_cvt_pk_bf16_f32 v245, v30, v31
	v_max_f32_e32 v0, 0, v0
	v_max_f32_e32 v1, 0, v1
	v_mul_f32_e32 v0, v0, v0
	v_mul_f32_e32 v1, v1, v1
	v_cvt_pk_bf16_f32 v246, v0, v1
	v_max_f32_e32 v2, 0, v2
	v_max_f32_e32 v3, 0, v3
	v_mul_f32_e32 v2, v2, v2
	v_mul_f32_e32 v3, v3, v3
	v_cvt_pk_bf16_f32 v247, v2, v3
	v_max_f32_e32 v4, 0, v4
	v_max_f32_e32 v5, 0, v5
	v_mul_f32_e32 v4, v4, v4
	v_mul_f32_e32 v5, v5, v5
	v_cvt_pk_bf16_f32 v248, v4, v5
	v_max_f32_e32 v6, 0, v6
	v_max_f32_e32 v7, 0, v7
	v_mul_f32_e32 v6, v6, v6
	v_mul_f32_e32 v7, v7, v7
	v_cvt_pk_bf16_f32 v249, v6, v7
	v_max_f32_e32 v8, 0, v8
	v_max_f32_e32 v9, 0, v9
	v_mul_f32_e32 v8, v8, v8
	v_mul_f32_e32 v9, v9, v9
	v_cvt_pk_bf16_f32 v250, v8, v9
	v_max_f32_e32 v10, 0, v10
	v_max_f32_e32 v11, 0, v11
	v_mul_f32_e32 v10, v10, v10
	v_mul_f32_e32 v11, v11, v11
	v_cvt_pk_bf16_f32 v251, v10, v11
	v_max_f32_e32 v12, 0, v12
	v_max_f32_e32 v13, 0, v13
	v_mul_f32_e32 v12, v12, v12
	v_mul_f32_e32 v13, v13, v13
	v_cvt_pk_bf16_f32 v252, v12, v13
	v_max_f32_e32 v14, 0, v14
	v_max_f32_e32 v15, 0, v15
	v_mul_f32_e32 v14, v14, v14
	v_mul_f32_e32 v15, v15, v15
	v_cvt_pk_bf16_f32 v253, v14, v15
	s_add_i32 s57, s57, s22
	s_add_i32 s56, s56, s22
	s_cmpk_lt_u32 s57, 0x240
	s_cbranch_scc1 .LBB0_996
	v_and_b32_e32 v3, 15, v182
	v_lshrrev_b32_e32 v4, 4, v182
	v_mul_u32_u24_e32 v2, 0x2000, v4
	v_lshl_add_u32 v2, v3, 4, v2
	v_mul_u32_u24_e32 v1, 0x110, v4
	v_lshl_add_u32 v1, v3, 4, v1
	v_lshrrev_b32_e32 v3, 7, v182
	v_bfe_u32 v4, v182, 5, 1
	v_lshlrev_b32_e32 v3, 6, v3
	v_lshl_or_b32 v3, v4, 2, v3
	v_mul_u32_u24_e32 v3, 136, v3
	v_and_b32_e32 v4, 0x5f, v182
	v_add_lshl_u32 v0, v3, v4, 1
	s_barrier
	ds_write_b16 v0, v190
	ds_write_b16_d16_hi v0, v190 offset:272
	ds_write_b16 v0, v191 offset:544
	ds_write_b16_d16_hi v0, v191 offset:816
	ds_write_b16 v0, v192 offset:2176
	ds_write_b16_d16_hi v0, v192 offset:2448
	ds_write_b16 v0, v193 offset:2720
	ds_write_b16_d16_hi v0, v193 offset:2992
	ds_write_b16 v0, v194 offset:4352
	ds_write_b16_d16_hi v0, v194 offset:4624
	ds_write_b16 v0, v195 offset:4896
	ds_write_b16_d16_hi v0, v195 offset:5168
	ds_write_b16 v0, v196 offset:6528
	ds_write_b16_d16_hi v0, v196 offset:6800
	ds_write_b16 v0, v197 offset:7072
	ds_write_b16_d16_hi v0, v197 offset:7344
	ds_write_b16 v0, v198 offset:64
	ds_write_b16_d16_hi v0, v198 offset:336
	ds_write_b16 v0, v199 offset:608
	ds_write_b16_d16_hi v0, v199 offset:880
	ds_write_b16 v0, v200 offset:2240
	ds_write_b16_d16_hi v0, v200 offset:2512
	ds_write_b16 v0, v201 offset:2784
	ds_write_b16_d16_hi v0, v201 offset:3056
	ds_write_b16 v0, v202 offset:4416
	ds_write_b16_d16_hi v0, v202 offset:4688
	ds_write_b16 v0, v203 offset:4960
	ds_write_b16_d16_hi v0, v203 offset:5232
	ds_write_b16 v0, v204 offset:6592
	ds_write_b16_d16_hi v0, v204 offset:6864
	ds_write_b16 v0, v205 offset:7136
	ds_write_b16_d16_hi v0, v205 offset:7408
	ds_write_b16 v0, v206 offset:8704
	ds_write_b16_d16_hi v0, v206 offset:8976
	ds_write_b16 v0, v207 offset:9248
	ds_write_b16_d16_hi v0, v207 offset:9520
	ds_write_b16 v0, v208 offset:10880
	ds_write_b16_d16_hi v0, v208 offset:11152
	ds_write_b16 v0, v209 offset:11424
	ds_write_b16_d16_hi v0, v209 offset:11696
	ds_write_b16 v0, v210 offset:13056
	ds_write_b16_d16_hi v0, v210 offset:13328
	ds_write_b16 v0, v211 offset:13600
	ds_write_b16_d16_hi v0, v211 offset:13872
	ds_write_b16 v0, v212 offset:15232
	ds_write_b16_d16_hi v0, v212 offset:15504
	ds_write_b16 v0, v213 offset:15776
	ds_write_b16_d16_hi v0, v213 offset:16048
	ds_write_b16 v0, v214 offset:8768
	ds_write_b16_d16_hi v0, v214 offset:9040
	ds_write_b16 v0, v215 offset:9312
	ds_write_b16_d16_hi v0, v215 offset:9584
	ds_write_b16 v0, v216 offset:10944
	ds_write_b16_d16_hi v0, v216 offset:11216
	ds_write_b16 v0, v217 offset:11488
	ds_write_b16_d16_hi v0, v217 offset:11760
	ds_write_b16 v0, v218 offset:13120
	ds_write_b16_d16_hi v0, v218 offset:13392
	ds_write_b16 v0, v219 offset:13664
	ds_write_b16_d16_hi v0, v219 offset:13936
	ds_write_b16 v0, v220 offset:15296
	ds_write_b16_d16_hi v0, v220 offset:15568
	ds_write_b16 v0, v221 offset:15840
	ds_write_b16_d16_hi v0, v221 offset:16112
	s_waitcnt lgkmcnt(0)
	s_barrier
	ds_read_b128 v[8:11], v1
	ds_read_b128 v[12:15], v1 offset:4352
	ds_read_b128 v[16:19], v1 offset:8704
	ds_read_b128 v[20:23], v1 offset:13056
	ds_read_b128 v[24:27], v1 offset:17408
	ds_read_b128 v[28:31], v1 offset:21760
	ds_read_b128 v[32:35], v1 offset:26112
	ds_read_b128 v[36:39], v1 offset:30464
	s_add_u32 s38, s44, 0x0
	s_addc_u32 s39, s45, 0
	s_waitcnt lgkmcnt(7)
	global_store_dwordx4 v2, v[8:11], s[38:39]
	s_add_u32 s38, s44, 0x20000
	s_addc_u32 s39, s45, 0
	s_waitcnt lgkmcnt(6)
	global_store_dwordx4 v2, v[12:15], s[38:39]
	s_add_u32 s38, s44, 0x40000
	s_addc_u32 s39, s45, 0
	s_waitcnt lgkmcnt(5)
	global_store_dwordx4 v2, v[16:19], s[38:39]
	s_add_u32 s38, s44, 0x60000
	s_addc_u32 s39, s45, 0
	s_waitcnt lgkmcnt(4)
	global_store_dwordx4 v2, v[20:23], s[38:39]
	s_add_u32 s38, s44, 0x100000
	s_addc_u32 s39, s45, 0
	s_waitcnt lgkmcnt(3)
	global_store_dwordx4 v2, v[24:27], s[38:39]
	s_add_u32 s38, s44, 0x120000
	s_addc_u32 s39, s45, 0
	s_waitcnt lgkmcnt(2)
	global_store_dwordx4 v2, v[28:31], s[38:39]
	s_add_u32 s38, s44, 0x140000
	s_addc_u32 s39, s45, 0
	s_waitcnt lgkmcnt(1)
	global_store_dwordx4 v2, v[32:35], s[38:39]
	s_add_u32 s38, s44, 0x160000
	s_addc_u32 s39, s45, 0
	s_waitcnt lgkmcnt(0)
	global_store_dwordx4 v2, v[36:39], s[38:39]
	s_barrier
	ds_write_b16 v0, v222
	ds_write_b16_d16_hi v0, v222 offset:272
	ds_write_b16 v0, v223 offset:544
	ds_write_b16_d16_hi v0, v223 offset:816
	ds_write_b16 v0, v224 offset:2176
	ds_write_b16_d16_hi v0, v224 offset:2448
	ds_write_b16 v0, v225 offset:2720
	ds_write_b16_d16_hi v0, v225 offset:2992
	ds_write_b16 v0, v226 offset:4352
	ds_write_b16_d16_hi v0, v226 offset:4624
	ds_write_b16 v0, v227 offset:4896
	ds_write_b16_d16_hi v0, v227 offset:5168
	ds_write_b16 v0, v228 offset:6528
	ds_write_b16_d16_hi v0, v228 offset:6800
	ds_write_b16 v0, v229 offset:7072
	ds_write_b16_d16_hi v0, v229 offset:7344
	ds_write_b16 v0, v230 offset:64
	ds_write_b16_d16_hi v0, v230 offset:336
	ds_write_b16 v0, v231 offset:608
	ds_write_b16_d16_hi v0, v231 offset:880
	ds_write_b16 v0, v232 offset:2240
	ds_write_b16_d16_hi v0, v232 offset:2512
	ds_write_b16 v0, v233 offset:2784
	ds_write_b16_d16_hi v0, v233 offset:3056
	ds_write_b16 v0, v234 offset:4416
	ds_write_b16_d16_hi v0, v234 offset:4688
	ds_write_b16 v0, v235 offset:4960
	ds_write_b16_d16_hi v0, v235 offset:5232
	ds_write_b16 v0, v236 offset:6592
	ds_write_b16_d16_hi v0, v236 offset:6864
	ds_write_b16 v0, v237 offset:7136
	ds_write_b16_d16_hi v0, v237 offset:7408
	ds_write_b16 v0, v238 offset:8704
	ds_write_b16_d16_hi v0, v238 offset:8976
	ds_write_b16 v0, v239 offset:9248
	ds_write_b16_d16_hi v0, v239 offset:9520
	ds_write_b16 v0, v240 offset:10880
	ds_write_b16_d16_hi v0, v240 offset:11152
	ds_write_b16 v0, v241 offset:11424
	ds_write_b16_d16_hi v0, v241 offset:11696
	ds_write_b16 v0, v242 offset:13056
	ds_write_b16_d16_hi v0, v242 offset:13328
	ds_write_b16 v0, v243 offset:13600
	ds_write_b16_d16_hi v0, v243 offset:13872
	ds_write_b16 v0, v244 offset:15232
	ds_write_b16_d16_hi v0, v244 offset:15504
	ds_write_b16 v0, v245 offset:15776
	ds_write_b16_d16_hi v0, v245 offset:16048
	ds_write_b16 v0, v246 offset:8768
	ds_write_b16_d16_hi v0, v246 offset:9040
	ds_write_b16 v0, v247 offset:9312
	ds_write_b16_d16_hi v0, v247 offset:9584
	ds_write_b16 v0, v248 offset:10944
	ds_write_b16_d16_hi v0, v248 offset:11216
	ds_write_b16 v0, v249 offset:11488
	ds_write_b16_d16_hi v0, v249 offset:11760
	ds_write_b16 v0, v250 offset:13120
	ds_write_b16_d16_hi v0, v250 offset:13392
	ds_write_b16 v0, v251 offset:13664
	ds_write_b16_d16_hi v0, v251 offset:13936
	ds_write_b16 v0, v252 offset:15296
	ds_write_b16_d16_hi v0, v252 offset:15568
	ds_write_b16 v0, v253 offset:15840
	ds_write_b16_d16_hi v0, v253 offset:16112
	s_waitcnt lgkmcnt(0)
	s_barrier
	ds_read_b128 v[8:11], v1
	ds_read_b128 v[12:15], v1 offset:4352
	ds_read_b128 v[16:19], v1 offset:8704
	ds_read_b128 v[20:23], v1 offset:13056
	ds_read_b128 v[24:27], v1 offset:17408
	ds_read_b128 v[28:31], v1 offset:21760
	ds_read_b128 v[32:35], v1 offset:26112
	ds_read_b128 v[36:39], v1 offset:30464
	s_add_u32 s38, s44, 0x80000
	s_addc_u32 s39, s45, 0
	s_waitcnt lgkmcnt(7)
	global_store_dwordx4 v2, v[8:11], s[38:39]
	s_add_u32 s38, s44, 0xa0000
	s_addc_u32 s39, s45, 0
	s_waitcnt lgkmcnt(6)
	global_store_dwordx4 v2, v[12:15], s[38:39]
	s_add_u32 s38, s44, 0xc0000
	s_addc_u32 s39, s45, 0
	s_waitcnt lgkmcnt(5)
	global_store_dwordx4 v2, v[16:19], s[38:39]
	s_add_u32 s38, s44, 0xe0000
	s_addc_u32 s39, s45, 0
	s_waitcnt lgkmcnt(4)
	global_store_dwordx4 v2, v[20:23], s[38:39]
	s_add_u32 s38, s44, 0x180000
	s_addc_u32 s39, s45, 0
	s_waitcnt lgkmcnt(3)
	global_store_dwordx4 v2, v[24:27], s[38:39]
	s_add_u32 s38, s44, 0x1a0000
	s_addc_u32 s39, s45, 0
	s_waitcnt lgkmcnt(2)
	global_store_dwordx4 v2, v[28:31], s[38:39]
	s_add_u32 s38, s44, 0x1c0000
	s_addc_u32 s39, s45, 0
	s_waitcnt lgkmcnt(1)
	global_store_dwordx4 v2, v[32:35], s[38:39]
	s_add_u32 s38, s44, 0x1e0000
	s_addc_u32 s39, s45, 0
	s_waitcnt lgkmcnt(0)
	global_store_dwordx4 v2, v[36:39], s[38:39]
	s_mov_b32 s43, 0
	s_branch .LBB0_989

.LBB0_1284:
	ds_read_b128 v[216:219], v176 offset:36864
	ds_read_b128 v[200:203], v188
	ds_read_b128 v[220:223], v176 offset:41472
	ds_read_b128 v[204:207], v188 offset:4608
	ds_read_b128 v[208:211], v188 offset:9216
	ds_read_b128 v[212:215], v187
	s_waitcnt lgkmcnt(4)
	v_mfma_f32_32x32x16_bf16 v[112:127], v[200:203], v[216:219], v[112:127]
	ds_read_b128 v[240:243], v176 offset:36896
	global_load_dwordx4 v[140:143], v190, s[44:45]
	s_waitcnt lgkmcnt(4)
	v_mfma_f32_32x32x16_bf16 v[96:111], v[200:203], v[220:223], v[96:111]
	ds_read_b128 v[224:227], v188 offset:32
	global_load_dwordx4 v[164:167], v190, s[42:43]
	s_waitcnt lgkmcnt(4)
	v_mfma_f32_32x32x16_bf16 v[80:95], v[204:207], v[216:219], v[80:95]
	ds_read_b128 v[244:247], v176 offset:41504
	global_load_dwordx4 v[128:131], v191, s[42:43]
	s_waitcnt lgkmcnt(5)
	v_mfma_f32_32x32x16_bf16 v[64:79], v[204:207], v[220:223], v[64:79]
	ds_read_b128 v[228:231], v188 offset:4640
	global_load_dwordx4 v[132:135], v192, s[42:43]
	s_waitcnt lgkmcnt(5)
	v_mfma_f32_32x32x16_bf16 v[48:63], v[208:211], v[216:219], v[48:63]
	ds_read_b128 v[232:235], v188 offset:9248
	global_load_dwordx4 v[136:139], v193, s[42:43]
	s_waitcnt lgkmcnt(6)
	v_mfma_f32_32x32x16_bf16 v[32:47], v[208:211], v[220:223], v[32:47]
	ds_read_b128 v[236:239], v187 offset:32
	global_load_dwordx4 v[144:147], v194, s[42:43]
	s_waitcnt lgkmcnt(6)
	v_mfma_f32_32x32x16_bf16 v[16:31], v[212:215], v[216:219], v[16:31]
	global_load_dwordx4 v[148:151], v195, s[42:43]
	global_load_dwordx4 v[152:155], v196, s[42:43]
	s_waitcnt lgkmcnt(6)
	v_mfma_f32_32x32x16_bf16 v[0:15], v[212:215], v[220:223], v[0:15]
	global_load_dwordx4 v[156:159], v197, s[42:43]
	global_load_dwordx4 v[160:163], v191, s[44:45]
	s_waitcnt lgkmcnt(4)
	v_mfma_f32_32x32x16_bf16 v[112:127], v[224:227], v[240:243], v[112:127]
	ds_read_b128 v[200:203], v188 offset:64
	global_load_dwordx4 v[168:171], v192, s[44:45]
	s_waitcnt lgkmcnt(4)
	v_mfma_f32_32x32x16_bf16 v[96:111], v[224:227], v[244:247], v[96:111]
	ds_read_b128 v[204:207], v188 offset:4672
	global_load_dwordx4 v[172:175], v193, s[44:45]
	s_add_u32 s42, s42, 0x80
	s_addc_u32 s43, s43, 0
	s_add_u32 s44, s44, 0x80
	s_addc_u32 s45, s45, 0
	s_add_u32 s16, s16, 0x80
	s_waitcnt lgkmcnt(4)
	v_mfma_f32_32x32x16_bf16 v[80:95], v[228:231], v[240:243], v[80:95]
	ds_read_b128 v[208:211], v188 offset:9280
	s_waitcnt lgkmcnt(5)
	v_mfma_f32_32x32x16_bf16 v[64:79], v[228:231], v[244:247], v[64:79]
	ds_read_b128 v[212:215], v187 offset:64
	s_waitcnt lgkmcnt(5)
	v_mfma_f32_32x32x16_bf16 v[48:63], v[232:235], v[240:243], v[48:63]
	ds_read_b128 v[216:219], v176 offset:36928
	s_waitcnt lgkmcnt(6)
	v_mfma_f32_32x32x16_bf16 v[32:47], v[232:235], v[244:247], v[32:47]
	ds_read_b128 v[220:223], v176 offset:41536
	s_waitcnt lgkmcnt(6)
	v_mfma_f32_32x32x16_bf16 v[16:31], v[236:239], v[240:243], v[16:31]
	s_waitcnt lgkmcnt(6)
	v_mfma_f32_32x32x16_bf16 v[0:15], v[236:239], v[244:247], v[0:15]
	s_waitcnt lgkmcnt(1)
	v_mfma_f32_32x32x16_bf16 v[112:127], v[200:203], v[216:219], v[112:127]
	ds_read_b128 v[224:227], v188 offset:96
	s_waitcnt lgkmcnt(1)
	v_mfma_f32_32x32x16_bf16 v[96:111], v[200:203], v[220:223], v[96:111]
	ds_read_b128 v[228:231], v188 offset:4704
	s_waitcnt lgkmcnt(3)
	v_mfma_f32_32x32x16_bf16 v[80:95], v[204:207], v[216:219], v[80:95]
	ds_read_b128 v[232:235], v188 offset:9312
	s_waitcnt lgkmcnt(3)
	v_mfma_f32_32x32x16_bf16 v[64:79], v[204:207], v[220:223], v[64:79]
	ds_read_b128 v[236:239], v187 offset:96
	s_waitcnt lgkmcnt(5)
	v_mfma_f32_32x32x16_bf16 v[48:63], v[208:211], v[216:219], v[48:63]
	ds_read_b128 v[240:243], v176 offset:36960
	s_waitcnt lgkmcnt(5)
	v_mfma_f32_32x32x16_bf16 v[32:47], v[208:211], v[220:223], v[32:47]
	ds_read_b128 v[244:247], v176 offset:41568
	s_waitcnt lgkmcnt(7)
	v_mfma_f32_32x32x16_bf16 v[16:31], v[212:215], v[216:219], v[16:31]
	s_waitcnt lgkmcnt(6)
	v_mfma_f32_32x32x16_bf16 v[0:15], v[212:215], v[220:223], v[0:15]
	s_waitcnt lgkmcnt(0)
	s_barrier
	s_waitcnt vmcnt(0)
	s_waitcnt lgkmcnt(1)
	v_mfma_f32_32x32x16_bf16 v[112:127], v[224:227], v[240:243], v[112:127]
	ds_write_b128 v189, v[164:167]
	ds_write_b128 v189, v[128:131] offset:4608
	s_waitcnt lgkmcnt(2)
	v_mfma_f32_32x32x16_bf16 v[96:111], v[224:227], v[244:247], v[96:111]
	ds_write_b128 v189, v[132:135] offset:9216
	s_waitcnt lgkmcnt(4)
	v_mfma_f32_32x32x16_bf16 v[80:95], v[228:231], v[240:243], v[80:95]
	ds_write_b128 v189, v[136:139] offset:13824
	ds_write_b128 v189, v[144:147] offset:18432
	s_waitcnt lgkmcnt(5)
	v_mfma_f32_32x32x16_bf16 v[64:79], v[228:231], v[244:247], v[64:79]
	ds_write_b128 v189, v[148:151] offset:23040
	s_waitcnt lgkmcnt(7)
	v_mfma_f32_32x32x16_bf16 v[48:63], v[232:235], v[240:243], v[48:63]
	ds_write_b128 v189, v[152:155] offset:27648
	ds_write_b128 v189, v[156:159] offset:32256
	s_waitcnt lgkmcnt(8)
	v_mfma_f32_32x32x16_bf16 v[32:47], v[232:235], v[244:247], v[32:47]
	ds_write_b128 v189, v[140:143] offset:36864
	s_waitcnt lgkmcnt(10)
	v_mfma_f32_32x32x16_bf16 v[16:31], v[236:239], v[240:243], v[16:31]
	ds_write_b128 v189, v[160:163] offset:41472
	ds_write_b128 v189, v[168:171] offset:46080
	s_waitcnt lgkmcnt(11)
	v_mfma_f32_32x32x16_bf16 v[0:15], v[236:239], v[244:247], v[0:15]
	ds_write_b128 v189, v[172:175] offset:50688
	s_waitcnt lgkmcnt(0)
	s_barrier
	s_cmpk_lg_i32 s16, 0x780
	s_cbranch_scc1 .LBB0_1284
	ds_read_b128 v[216:219], v176 offset:36864
	ds_read_b128 v[200:203], v188
	ds_read_b128 v[220:223], v176 offset:41472
	ds_read_b128 v[204:207], v188 offset:4608
	ds_read_b128 v[208:211], v188 offset:9216
	ds_read_b128 v[212:215], v187
	s_waitcnt lgkmcnt(4)
	v_mfma_f32_32x32x16_bf16 v[112:127], v[200:203], v[216:219], v[112:127]
	ds_read_b128 v[240:243], v176 offset:36896
	s_waitcnt lgkmcnt(4)
	v_mfma_f32_32x32x16_bf16 v[96:111], v[200:203], v[220:223], v[96:111]
	ds_read_b128 v[224:227], v188 offset:32
	s_waitcnt lgkmcnt(4)
	v_mfma_f32_32x32x16_bf16 v[80:95], v[204:207], v[216:219], v[80:95]
	ds_read_b128 v[244:247], v176 offset:41504
	s_waitcnt lgkmcnt(5)
	v_mfma_f32_32x32x16_bf16 v[64:79], v[204:207], v[220:223], v[64:79]
	ds_read_b128 v[228:231], v188 offset:4640
	s_waitcnt lgkmcnt(5)
	v_mfma_f32_32x32x16_bf16 v[48:63], v[208:211], v[216:219], v[48:63]
	ds_read_b128 v[232:235], v188 offset:9248
	s_waitcnt lgkmcnt(6)
	v_mfma_f32_32x32x16_bf16 v[32:47], v[208:211], v[220:223], v[32:47]
	ds_read_b128 v[236:239], v187 offset:32
	s_waitcnt lgkmcnt(6)
	v_mfma_f32_32x32x16_bf16 v[16:31], v[212:215], v[216:219], v[16:31]
	s_waitcnt lgkmcnt(6)
	v_mfma_f32_32x32x16_bf16 v[0:15], v[212:215], v[220:223], v[0:15]
	s_waitcnt lgkmcnt(4)
	v_mfma_f32_32x32x16_bf16 v[112:127], v[224:227], v[240:243], v[112:127]
	ds_read_b128 v[200:203], v188 offset:64
	s_waitcnt lgkmcnt(4)
	v_mfma_f32_32x32x16_bf16 v[96:111], v[224:227], v[244:247], v[96:111]
	ds_read_b128 v[204:207], v188 offset:4672
	s_waitcnt lgkmcnt(4)
	v_mfma_f32_32x32x16_bf16 v[80:95], v[228:231], v[240:243], v[80:95]
	ds_read_b128 v[208:211], v188 offset:9280
	s_waitcnt lgkmcnt(5)
	v_mfma_f32_32x32x16_bf16 v[64:79], v[228:231], v[244:247], v[64:79]
	ds_read_b128 v[212:215], v187 offset:64
	s_waitcnt lgkmcnt(5)
	v_mfma_f32_32x32x16_bf16 v[48:63], v[232:235], v[240:243], v[48:63]
	ds_read_b128 v[216:219], v176 offset:36928
	s_waitcnt lgkmcnt(6)
	v_mfma_f32_32x32x16_bf16 v[32:47], v[232:235], v[244:247], v[32:47]
	ds_read_b128 v[220:223], v176 offset:41536
	s_waitcnt lgkmcnt(6)
	v_mfma_f32_32x32x16_bf16 v[16:31], v[236:239], v[240:243], v[16:31]
	s_waitcnt lgkmcnt(6)
	v_mfma_f32_32x32x16_bf16 v[0:15], v[236:239], v[244:247], v[0:15]
	s_waitcnt lgkmcnt(1)
	v_mfma_f32_32x32x16_bf16 v[112:127], v[200:203], v[216:219], v[112:127]
	ds_read_b128 v[224:227], v188 offset:96
	s_waitcnt lgkmcnt(1)
	v_mfma_f32_32x32x16_bf16 v[96:111], v[200:203], v[220:223], v[96:111]
	ds_read_b128 v[228:231], v188 offset:4704
	s_waitcnt lgkmcnt(3)
	v_mfma_f32_32x32x16_bf16 v[80:95], v[204:207], v[216:219], v[80:95]
	ds_read_b128 v[232:235], v188 offset:9312
	s_waitcnt lgkmcnt(3)
	v_mfma_f32_32x32x16_bf16 v[64:79], v[204:207], v[220:223], v[64:79]
	ds_read_b128 v[236:239], v187 offset:96
	s_waitcnt lgkmcnt(5)
	v_mfma_f32_32x32x16_bf16 v[48:63], v[208:211], v[216:219], v[48:63]
	ds_read_b128 v[240:243], v176 offset:36960
	s_waitcnt lgkmcnt(5)
	v_mfma_f32_32x32x16_bf16 v[32:47], v[208:211], v[220:223], v[32:47]
	ds_read_b128 v[244:247], v176 offset:41568
	s_waitcnt lgkmcnt(7)
	v_mfma_f32_32x32x16_bf16 v[16:31], v[212:215], v[216:219], v[16:31]
	s_waitcnt lgkmcnt(6)
	v_mfma_f32_32x32x16_bf16 v[0:15], v[212:215], v[220:223], v[0:15]
	s_waitcnt lgkmcnt(1)
	v_mfma_f32_32x32x16_bf16 v[112:127], v[224:227], v[240:243], v[112:127]
	s_waitcnt lgkmcnt(0)
	v_mfma_f32_32x32x16_bf16 v[96:111], v[224:227], v[244:247], v[96:111]
	s_waitcnt lgkmcnt(1)
	v_mfma_f32_32x32x16_bf16 v[80:95], v[228:231], v[240:243], v[80:95]
	s_waitcnt lgkmcnt(0)
	v_mfma_f32_32x32x16_bf16 v[64:79], v[228:231], v[244:247], v[64:79]
	s_waitcnt lgkmcnt(1)
	v_mfma_f32_32x32x16_bf16 v[48:63], v[232:235], v[240:243], v[48:63]
	s_waitcnt lgkmcnt(0)
	v_mfma_f32_32x32x16_bf16 v[32:47], v[232:235], v[244:247], v[32:47]
	s_waitcnt lgkmcnt(1)
	v_mfma_f32_32x32x16_bf16 v[16:31], v[236:239], v[240:243], v[16:31]
	s_waitcnt lgkmcnt(0)
	v_mfma_f32_32x32x16_bf16 v[0:15], v[236:239], v[244:247], v[0:15]
	s_mul_i32 s41, s12, 0x1240
	s_add_u32 s42, s30, s41
	s_addc_u32 s43, s31, 0
	s_lshl_b32 s41, s8, 1
	s_add_u32 s42, s42, s41
	s_addc_u32 s43, s43, 0
	s_add_u32 s42, s42, 0x7157900
	s_addc_u32 s43, s43, 0
	v_and_b32_e32 v131, 15, v182
	v_lshrrev_b32_e32 v172, 4, v182
	v_lshl_add_u32 v130, v131, 3, s8
	s_movk_i32 s41, 0x920
	v_cmp_gt_u32_e64 s[44:45], s41, v130
	v_mul_u32_u24_e32 v164, 0x1240, v172
	v_lshl_add_u32 v164, v131, 4, v164
	v_add_u32_e32 v165, 0x12400, v164
	v_add_u32_e32 v166, 0x24800, v164
	v_add_u32_e32 v167, 0x36c00, v164
	v_add_u32_e32 v168, 0x92000, v164
	v_add_u32_e32 v169, 0xa4400, v164
	v_add_u32_e32 v170, 0xb6800, v164
	v_add_u32_e32 v171, 0xc8c00, v164
	v_mul_u32_u24_e32 v129, 0x110, v172
	v_lshl_add_u32 v129, v131, 4, v129
	v_lshrrev_b32_e32 v131, 7, v182
	v_bfe_u32 v172, v182, 5, 1
	v_lshlrev_b32_e32 v131, 6, v131
	v_lshl_or_b32 v131, v172, 2, v131
	v_mul_u32_u24_e32 v131, 136, v131
	v_and_b32_e32 v172, 0x5f, v182
	v_add_lshl_u32 v128, v131, v172, 1
	s_barrier
	v_cvt_pk_bf16_f32 v112, v112, v113
	v_cvt_pk_bf16_f32 v114, v114, v115
	v_cvt_pk_bf16_f32 v116, v116, v117
	v_cvt_pk_bf16_f32 v118, v118, v119
	v_cvt_pk_bf16_f32 v120, v120, v121
	v_cvt_pk_bf16_f32 v122, v122, v123
	v_cvt_pk_bf16_f32 v124, v124, v125
	v_cvt_pk_bf16_f32 v126, v126, v127
	v_cvt_pk_bf16_f32 v96, v96, v97
	v_cvt_pk_bf16_f32 v98, v98, v99
	v_cvt_pk_bf16_f32 v100, v100, v101
	v_cvt_pk_bf16_f32 v102, v102, v103
	v_cvt_pk_bf16_f32 v104, v104, v105
	v_cvt_pk_bf16_f32 v106, v106, v107
	v_cvt_pk_bf16_f32 v108, v108, v109
	v_cvt_pk_bf16_f32 v110, v110, v111
	v_cvt_pk_bf16_f32 v80, v80, v81
	v_cvt_pk_bf16_f32 v82, v82, v83
	v_cvt_pk_bf16_f32 v84, v84, v85
	v_cvt_pk_bf16_f32 v86, v86, v87
	v_cvt_pk_bf16_f32 v88, v88, v89
	v_cvt_pk_bf16_f32 v90, v90, v91
	v_cvt_pk_bf16_f32 v92, v92, v93
	v_cvt_pk_bf16_f32 v94, v94, v95
	v_cvt_pk_bf16_f32 v64, v64, v65
	v_cvt_pk_bf16_f32 v66, v66, v67
	v_cvt_pk_bf16_f32 v68, v68, v69
	v_cvt_pk_bf16_f32 v70, v70, v71
	v_cvt_pk_bf16_f32 v72, v72, v73
	v_cvt_pk_bf16_f32 v74, v74, v75
	v_cvt_pk_bf16_f32 v76, v76, v77
	v_cvt_pk_bf16_f32 v78, v78, v79
	ds_write_b16 v128, v112
	ds_write_b16_d16_hi v128, v112 offset:272
	ds_write_b16 v128, v114 offset:544
	ds_write_b16_d16_hi v128, v114 offset:816
	ds_write_b16 v128, v116 offset:2176
	ds_write_b16_d16_hi v128, v116 offset:2448
	ds_write_b16 v128, v118 offset:2720
	ds_write_b16_d16_hi v128, v118 offset:2992
	ds_write_b16 v128, v120 offset:4352
	ds_write_b16_d16_hi v128, v120 offset:4624
	ds_write_b16 v128, v122 offset:4896
	ds_write_b16_d16_hi v128, v122 offset:5168
	ds_write_b16 v128, v124 offset:6528
	ds_write_b16_d16_hi v128, v124 offset:6800
	ds_write_b16 v128, v126 offset:7072
	ds_write_b16_d16_hi v128, v126 offset:7344
	ds_write_b16 v128, v96 offset:64
	ds_write_b16_d16_hi v128, v96 offset:336
	ds_write_b16 v128, v98 offset:608
	ds_write_b16_d16_hi v128, v98 offset:880
	ds_write_b16 v128, v100 offset:2240
	ds_write_b16_d16_hi v128, v100 offset:2512
	ds_write_b16 v128, v102 offset:2784
	ds_write_b16_d16_hi v128, v102 offset:3056
	ds_write_b16 v128, v104 offset:4416
	ds_write_b16_d16_hi v128, v104 offset:4688
	ds_write_b16 v128, v106 offset:4960
	ds_write_b16_d16_hi v128, v106 offset:5232
	ds_write_b16 v128, v108 offset:6592
	ds_write_b16_d16_hi v128, v108 offset:6864
	ds_write_b16 v128, v110 offset:7136
	ds_write_b16_d16_hi v128, v110 offset:7408
	ds_write_b16 v128, v80 offset:8704
	ds_write_b16_d16_hi v128, v80 offset:8976
	ds_write_b16 v128, v82 offset:9248
	ds_write_b16_d16_hi v128, v82 offset:9520
	ds_write_b16 v128, v84 offset:10880
	ds_write_b16_d16_hi v128, v84 offset:11152
	ds_write_b16 v128, v86 offset:11424
	ds_write_b16_d16_hi v128, v86 offset:11696
	ds_write_b16 v128, v88 offset:13056
	ds_write_b16_d16_hi v128, v88 offset:13328
	ds_write_b16 v128, v90 offset:13600
	ds_write_b16_d16_hi v128, v90 offset:13872
	ds_write_b16 v128, v92 offset:15232
	ds_write_b16_d16_hi v128, v92 offset:15504
	ds_write_b16 v128, v94 offset:15776
	ds_write_b16_d16_hi v128, v94 offset:16048
	ds_write_b16 v128, v64 offset:8768
	ds_write_b16_d16_hi v128, v64 offset:9040
	ds_write_b16 v128, v66 offset:9312
	ds_write_b16_d16_hi v128, v66 offset:9584
	ds_write_b16 v128, v68 offset:10944
	ds_write_b16_d16_hi v128, v68 offset:11216
	ds_write_b16 v128, v70 offset:11488
	ds_write_b16_d16_hi v128, v70 offset:11760
	ds_write_b16 v128, v72 offset:13120
	ds_write_b16_d16_hi v128, v72 offset:13392
	ds_write_b16 v128, v74 offset:13664
	ds_write_b16_d16_hi v128, v74 offset:13936
	ds_write_b16 v128, v76 offset:15296
	ds_write_b16_d16_hi v128, v76 offset:15568
	ds_write_b16 v128, v78 offset:15840
	ds_write_b16_d16_hi v128, v78 offset:16112
	s_waitcnt lgkmcnt(0)
	s_barrier
	ds_read_b128 v[132:135], v129
	ds_read_b128 v[136:139], v129 offset:4352
	ds_read_b128 v[140:143], v129 offset:8704
	ds_read_b128 v[144:147], v129 offset:13056
	ds_read_b128 v[148:151], v129 offset:17408
	ds_read_b128 v[152:155], v129 offset:21760
	ds_read_b128 v[156:159], v129 offset:26112
	ds_read_b128 v[160:163], v129 offset:30464
	v_cvt_pk_bf16_f32 v48, v48, v49
	v_cvt_pk_bf16_f32 v50, v50, v51
	v_cvt_pk_bf16_f32 v52, v52, v53
	v_cvt_pk_bf16_f32 v54, v54, v55
	v_cvt_pk_bf16_f32 v56, v56, v57
	v_cvt_pk_bf16_f32 v58, v58, v59
	v_cvt_pk_bf16_f32 v60, v60, v61
	v_cvt_pk_bf16_f32 v62, v62, v63
	v_cvt_pk_bf16_f32 v32, v32, v33
	v_cvt_pk_bf16_f32 v34, v34, v35
	v_cvt_pk_bf16_f32 v36, v36, v37
	v_cvt_pk_bf16_f32 v38, v38, v39
	v_cvt_pk_bf16_f32 v40, v40, v41
	v_cvt_pk_bf16_f32 v42, v42, v43
	v_cvt_pk_bf16_f32 v44, v44, v45
	v_cvt_pk_bf16_f32 v46, v46, v47
	v_cvt_pk_bf16_f32 v16, v16, v17
	v_cvt_pk_bf16_f32 v18, v18, v19
	v_cvt_pk_bf16_f32 v20, v20, v21
	v_cvt_pk_bf16_f32 v22, v22, v23
	v_cvt_pk_bf16_f32 v24, v24, v25
	v_cvt_pk_bf16_f32 v26, v26, v27
	v_cvt_pk_bf16_f32 v28, v28, v29
	v_cvt_pk_bf16_f32 v30, v30, v31
	v_cvt_pk_bf16_f32 v0, v0, v1
	v_cvt_pk_bf16_f32 v2, v2, v3
	v_cvt_pk_bf16_f32 v4, v4, v5
	v_cvt_pk_bf16_f32 v6, v6, v7
	v_cvt_pk_bf16_f32 v8, v8, v9
	v_cvt_pk_bf16_f32 v10, v10, v11
	v_cvt_pk_bf16_f32 v12, v12, v13
	v_cvt_pk_bf16_f32 v14, v14, v15
	s_and_saveexec_b64 s[46:47], s[44:45]
	s_waitcnt lgkmcnt(7)
	global_store_dwordx4 v164, v[132:135], s[42:43]
	s_waitcnt lgkmcnt(6)
	global_store_dwordx4 v165, v[136:139], s[42:43]
	s_waitcnt lgkmcnt(5)
	global_store_dwordx4 v166, v[140:143], s[42:43]
	s_waitcnt lgkmcnt(4)
	global_store_dwordx4 v167, v[144:147], s[42:43]
	s_waitcnt lgkmcnt(3)
	global_store_dwordx4 v168, v[148:151], s[42:43]
	s_waitcnt lgkmcnt(2)
	global_store_dwordx4 v169, v[152:155], s[42:43]
	s_waitcnt lgkmcnt(1)
	global_store_dwordx4 v170, v[156:159], s[42:43]
	s_waitcnt lgkmcnt(0)
	global_store_dwordx4 v171, v[160:163], s[42:43]
	s_or_b64 exec, exec, s[46:47]
	s_barrier
	ds_write_b16 v128, v48
	ds_write_b16_d16_hi v128, v48 offset:272
	ds_write_b16 v128, v50 offset:544
	ds_write_b16_d16_hi v128, v50 offset:816
	ds_write_b16 v128, v52 offset:2176
	ds_write_b16_d16_hi v128, v52 offset:2448
	ds_write_b16 v128, v54 offset:2720
	ds_write_b16_d16_hi v128, v54 offset:2992
	ds_write_b16 v128, v56 offset:4352
	ds_write_b16_d16_hi v128, v56 offset:4624
	ds_write_b16 v128, v58 offset:4896
	ds_write_b16_d16_hi v128, v58 offset:5168
	ds_write_b16 v128, v60 offset:6528
	ds_write_b16_d16_hi v128, v60 offset:6800
	ds_write_b16 v128, v62 offset:7072
	ds_write_b16_d16_hi v128, v62 offset:7344
	ds_write_b16 v128, v32 offset:64
	ds_write_b16_d16_hi v128, v32 offset:336
	ds_write_b16 v128, v34 offset:608
	ds_write_b16_d16_hi v128, v34 offset:880
	ds_write_b16 v128, v36 offset:2240
	ds_write_b16_d16_hi v128, v36 offset:2512
	ds_write_b16 v128, v38 offset:2784
	ds_write_b16_d16_hi v128, v38 offset:3056
	ds_write_b16 v128, v40 offset:4416
	ds_write_b16_d16_hi v128, v40 offset:4688
	ds_write_b16 v128, v42 offset:4960
	ds_write_b16_d16_hi v128, v42 offset:5232
	ds_write_b16 v128, v44 offset:6592
	ds_write_b16_d16_hi v128, v44 offset:6864
	ds_write_b16 v128, v46 offset:7136
	ds_write_b16_d16_hi v128, v46 offset:7408
	ds_write_b16 v128, v16 offset:8704
	ds_write_b16_d16_hi v128, v16 offset:8976
	ds_write_b16 v128, v18 offset:9248
	ds_write_b16_d16_hi v128, v18 offset:9520
	ds_write_b16 v128, v20 offset:10880
	ds_write_b16_d16_hi v128, v20 offset:11152
	ds_write_b16 v128, v22 offset:11424
	ds_write_b16_d16_hi v128, v22 offset:11696
	ds_write_b16 v128, v24 offset:13056
	ds_write_b16_d16_hi v128, v24 offset:13328
	ds_write_b16 v128, v26 offset:13600
	ds_write_b16_d16_hi v128, v26 offset:13872
	ds_write_b16 v128, v28 offset:15232
	ds_write_b16_d16_hi v128, v28 offset:15504
	ds_write_b16 v128, v30 offset:15776
	ds_write_b16_d16_hi v128, v30 offset:16048
	ds_write_b16 v128, v0 offset:8768
	ds_write_b16_d16_hi v128, v0 offset:9040
	ds_write_b16 v128, v2 offset:9312
	ds_write_b16_d16_hi v128, v2 offset:9584
	ds_write_b16 v128, v4 offset:10944
	ds_write_b16_d16_hi v128, v4 offset:11216
	ds_write_b16 v128, v6 offset:11488
	ds_write_b16_d16_hi v128, v6 offset:11760
	ds_write_b16 v128, v8 offset:13120
	ds_write_b16_d16_hi v128, v8 offset:13392
	ds_write_b16 v128, v10 offset:13664
	ds_write_b16_d16_hi v128, v10 offset:13936
	ds_write_b16 v128, v12 offset:15296
	ds_write_b16_d16_hi v128, v12 offset:15568
	ds_write_b16 v128, v14 offset:15840
	ds_write_b16_d16_hi v128, v14 offset:16112
	s_waitcnt lgkmcnt(0)
	s_barrier
	ds_read_b128 v[132:135], v129
	ds_read_b128 v[136:139], v129 offset:4352
	ds_read_b128 v[140:143], v129 offset:8704
	ds_read_b128 v[144:147], v129 offset:13056
	ds_read_b128 v[148:151], v129 offset:17408
	ds_read_b128 v[152:155], v129 offset:21760
	ds_read_b128 v[156:159], v129 offset:26112
	ds_read_b128 v[160:163], v129 offset:30464
	v_add_u32_e32 v164, 0x49000, v164
	v_add_u32_e32 v165, 0x49000, v165
	v_add_u32_e32 v166, 0x49000, v166
	v_add_u32_e32 v167, 0x49000, v167
	v_add_u32_e32 v168, 0x49000, v168
	v_add_u32_e32 v169, 0x49000, v169
	v_add_u32_e32 v170, 0x49000, v170
	v_add_u32_e32 v171, 0x49000, v171
	s_and_saveexec_b64 s[46:47], s[44:45]
	s_waitcnt lgkmcnt(7)
	global_store_dwordx4 v164, v[132:135], s[42:43]
	s_waitcnt lgkmcnt(6)
	global_store_dwordx4 v165, v[136:139], s[42:43]
	s_waitcnt lgkmcnt(5)
	global_store_dwordx4 v166, v[140:143], s[42:43]
	s_waitcnt lgkmcnt(4)
	global_store_dwordx4 v167, v[144:147], s[42:43]
	s_waitcnt lgkmcnt(3)
	global_store_dwordx4 v168, v[148:151], s[42:43]
	s_waitcnt lgkmcnt(2)
	global_store_dwordx4 v169, v[152:155], s[42:43]
	s_waitcnt lgkmcnt(1)
	global_store_dwordx4 v170, v[156:159], s[42:43]
	s_waitcnt lgkmcnt(0)
	global_store_dwordx4 v171, v[160:163], s[42:43]
	s_or_b64 exec, exec, s[46:47]
	s_branch .LBB0_1281

.LBB0_1976:
	s_and_b32 s6, s56, 7
	s_lshl_b32 s6, s6, 7
	s_add_i32 s6, s22, s6
	s_lshl_b32 s59, s6, 11
	s_lshr_b32 s6, s57, 3
	s_add_i32 s6, s20, s6
	s_lshr_b32 s6, s6, 3
	s_mul_i32 s6, s6, 9
	s_bfe_u32 s10, s57, 0x30003
	s_add_i32 s6, s6, s10
	s_and_b32 s10, s57, 7
	s_or_b32 s62, s10, s18
	s_mov_b64 s[10:11], s[30:31]
	v_mov_b32_e32 v0, v177
	s_lshl_b32 s6, s6, 8
	v_mbcnt_lo_u32_b32 v0, -1, v0
	v_mbcnt_hi_u32_b32 v0, -1, v0
	s_addk_i32 s6, 0x100
	v_add_u32_e32 v182, s33, v0
	s_lshl_b32 s58, s62, 7
	s_lshl_b64 s[12:13], s[6:7], 11
	v_ashrrev_i32_e32 v0, 3, v182
	v_lshlrev_b32_e32 v183, 3, v182
	s_add_u32 s60, s14, s12
	v_and_b32_e32 v6, 56, v183
	v_lshlrev_b32_e32 v1, 11, v0
	s_addc_u32 s61, s15, s13
	v_lshl_or_b32 v176, v6, 1, v1
	v_mul_lo_u32 v7, v0, s23
	v_lshl_add_u64 v[0:1], s[60:61], 0, v[176:177]
	v_add_co_u32_e32 v2, vcc, s24, v0
	s_lshl_b32 s62, s62, 18
	s_nop 0
	v_addc_co_u32_e32 v3, vcc, 0, v1, vcc
	v_add_co_u32_e32 v4, vcc, s25, v0
	s_add_u32 s62, s16, s62
	s_nop 0
	v_addc_co_u32_e32 v5, vcc, 0, v1, vcc
	global_load_dwordx4 v[128:131], v[2:3], off
	global_load_dwordx4 v[132:135], v[4:5], off
	v_add_co_u32_e32 v2, vcc, s26, v0
	s_addc_u32 s63, s17, 0
	s_nop 0
	v_addc_co_u32_e32 v3, vcc, 0, v1, vcc
	v_add_co_u32_e32 v4, vcc, s27, v0
	v_bfe_u32 v184, v182, 6, 1
	s_nop 0
	v_addc_co_u32_e32 v5, vcc, 0, v1, vcc
	global_load_dwordx4 v[136:139], v[2:3], off
	global_load_dwordx4 v[140:143], v[4:5], off
	v_add_co_u32_e32 v2, vcc, s34, v0
	v_and_b32_e32 v185, 31, v182
	s_nop 0
	v_addc_co_u32_e32 v3, vcc, 0, v1, vcc
	v_add_co_u32_e32 v4, vcc, s35, v0
	v_bfe_u32 v186, v182, 5, 1
	s_nop 0
	v_addc_co_u32_e32 v5, vcc, 0, v1, vcc
	v_add_co_u32_e32 v0, vcc, s36, v0
	global_load_dwordx4 v[144:147], v[2:3], off
	global_load_dwordx4 v[148:151], v[4:5], off
	v_addc_co_u32_e32 v1, vcc, 0, v1, vcc
	v_lshl_add_u64 v[2:3], s[62:63], 0, v[176:177]
	v_add_co_u32_e32 v4, vcc, s24, v2
	global_load_dwordx4 v[160:163], v176, s[60:61]
	global_load_dwordx4 v[152:155], v176, s[62:63]
	v_addc_co_u32_e32 v5, vcc, 0, v3, vcc
	global_load_dwordx4 v[156:159], v[0:1], off
	global_load_dwordx4 v[164:167], v[4:5], off
	v_add_co_u32_e32 v0, vcc, s25, v2
	s_add_u32 s60, s30, s59
	s_nop 0
	v_addc_co_u32_e32 v1, vcc, 0, v3, vcc
	v_add_co_u32_e32 v2, vcc, s26, v2
	s_addc_u32 s61, s31, 0
	s_nop 0
	v_addc_co_u32_e32 v3, vcc, 0, v3, vcc
	global_load_dwordx4 v[168:171], v[0:1], off
	global_load_dwordx4 v[172:175], v[2:3], off
	v_and_b32_e32 v0, 0xfffff9f, v182
	v_lshl_or_b32 v2, v184, 6, v185
	v_mul_lo_u32 v3, v0, s37
	v_or_b32_e32 v0, 0x60, v182
	s_add_u32 s12, s30, s12
	v_lshlrev_b32_e32 v1, 4, v186
	v_mul_lo_u32 v4, v0, s37
	v_mul_u32_u24_e32 v2, 0x90, v2
	s_addc_u32 s13, s31, s13
	v_mov_b32_e32 v0, 0
	v_add_lshl_u32 v189, v7, v6, 1
	v_lshl_add_u64 v[178:179], s[60:61], 0, v[176:177]
	v_lshl_add_u64 v[180:181], s[12:13], 0, v[176:177]
	s_mov_b64 s[12:13], 0
	v_add_u32_e32 v187, v1, v3
	v_add_u32_e32 v176, v1, v4
	v_add_u32_e32 v188, v1, v2
	v_mov_b32_e32 v1, v0
	v_mov_b32_e32 v2, v0
	v_mov_b32_e32 v3, v0
	v_mov_b32_e32 v4, v0
	v_mov_b32_e32 v5, v0
	v_mov_b32_e32 v6, v0
	v_mov_b32_e32 v7, v0
	v_mov_b32_e32 v8, v0
	v_mov_b32_e32 v9, v0
	v_mov_b32_e32 v10, v0
	v_mov_b32_e32 v11, v0
	v_mov_b32_e32 v12, v0
	v_mov_b32_e32 v13, v0
	v_mov_b32_e32 v14, v0
	v_mov_b32_e32 v15, v0
	v_mov_b32_e32 v16, v0
	v_mov_b32_e32 v17, v0
	v_mov_b32_e32 v18, v0
	v_mov_b32_e32 v19, v0
	v_mov_b32_e32 v20, v0
	v_mov_b32_e32 v21, v0
	v_mov_b32_e32 v22, v0
	v_mov_b32_e32 v23, v0
	v_mov_b32_e32 v24, v0
	v_mov_b32_e32 v25, v0
	v_mov_b32_e32 v26, v0
	v_mov_b32_e32 v27, v0
	v_mov_b32_e32 v28, v0
	v_mov_b32_e32 v29, v0
	v_mov_b32_e32 v30, v0
	v_mov_b32_e32 v31, v0
	v_mov_b32_e32 v32, v0
	v_mov_b32_e32 v33, v0
	v_mov_b32_e32 v34, v0
	v_mov_b32_e32 v35, v0
	v_mov_b32_e32 v36, v0
	v_mov_b32_e32 v37, v0
	v_mov_b32_e32 v38, v0
	v_mov_b32_e32 v39, v0
	v_mov_b32_e32 v40, v0
	v_mov_b32_e32 v41, v0
	v_mov_b32_e32 v42, v0
	v_mov_b32_e32 v43, v0
	v_mov_b32_e32 v44, v0
	v_mov_b32_e32 v45, v0
	v_mov_b32_e32 v46, v0
	v_mov_b32_e32 v47, v0
	v_mov_b32_e32 v48, v0
	v_mov_b32_e32 v49, v0
	v_mov_b32_e32 v50, v0
	v_mov_b32_e32 v51, v0
	v_mov_b32_e32 v52, v0
	v_mov_b32_e32 v53, v0
	v_mov_b32_e32 v54, v0
	v_mov_b32_e32 v55, v0
	v_mov_b32_e32 v56, v0
	v_mov_b32_e32 v57, v0
	v_mov_b32_e32 v58, v0
	v_mov_b32_e32 v59, v0
	v_mov_b32_e32 v60, v0
	v_mov_b32_e32 v61, v0
	v_mov_b32_e32 v62, v0
	v_mov_b32_e32 v63, v0
	v_mov_b32_e32 v64, v0
	v_mov_b32_e32 v65, v0
	v_mov_b32_e32 v66, v0
	v_mov_b32_e32 v67, v0
	v_mov_b32_e32 v68, v0
	v_mov_b32_e32 v69, v0
	v_mov_b32_e32 v70, v0
	v_mov_b32_e32 v71, v0
	v_mov_b32_e32 v72, v0
	v_mov_b32_e32 v73, v0
	v_mov_b32_e32 v74, v0
	v_mov_b32_e32 v75, v0
	v_mov_b32_e32 v76, v0
	v_mov_b32_e32 v77, v0
	v_mov_b32_e32 v78, v0
	v_mov_b32_e32 v79, v0
	v_mov_b32_e32 v80, v0
	v_mov_b32_e32 v81, v0
	v_mov_b32_e32 v82, v0
	v_mov_b32_e32 v83, v0
	v_mov_b32_e32 v84, v0
	v_mov_b32_e32 v85, v0
	v_mov_b32_e32 v86, v0
	v_mov_b32_e32 v87, v0
	v_mov_b32_e32 v88, v0
	v_mov_b32_e32 v89, v0
	v_mov_b32_e32 v90, v0
	v_mov_b32_e32 v91, v0
	v_mov_b32_e32 v92, v0
	v_mov_b32_e32 v93, v0
	v_mov_b32_e32 v94, v0
	v_mov_b32_e32 v95, v0
	v_mov_b32_e32 v96, v0
	v_mov_b32_e32 v97, v0
	v_mov_b32_e32 v98, v0
	v_mov_b32_e32 v99, v0
	v_mov_b32_e32 v100, v0
	v_mov_b32_e32 v101, v0
	v_mov_b32_e32 v102, v0
	v_mov_b32_e32 v103, v0
	v_mov_b32_e32 v104, v0
	v_mov_b32_e32 v105, v0
	v_mov_b32_e32 v106, v0
	v_mov_b32_e32 v107, v0
	v_mov_b32_e32 v108, v0
	v_mov_b32_e32 v109, v0
	v_mov_b32_e32 v110, v0
	v_mov_b32_e32 v111, v0
	v_mov_b32_e32 v112, v0
	v_mov_b32_e32 v113, v0
	v_mov_b32_e32 v114, v0
	v_mov_b32_e32 v115, v0
	v_mov_b32_e32 v116, v0
	v_mov_b32_e32 v117, v0
	v_mov_b32_e32 v118, v0
	v_mov_b32_e32 v119, v0
	v_mov_b32_e32 v120, v0
	v_mov_b32_e32 v121, v0
	v_mov_b32_e32 v122, v0
	v_mov_b32_e32 v123, v0
	v_mov_b32_e32 v124, v0
	v_mov_b32_e32 v125, v0
	v_mov_b32_e32 v126, v0
	v_mov_b32_e32 v127, v0
	s_cmp_eq_u32 s43, 0
	s_cbranch_scc1 .Lv5_a_3
	v_and_b32_e32 v3, 15, v182
	v_lshrrev_b32_e32 v4, 4, v182
	v_mul_u32_u24_e32 v2, 0x2000, v4
	v_lshl_add_u32 v2, v3, 4, v2
	v_mul_u32_u24_e32 v1, 0x110, v4
	v_lshl_add_u32 v1, v3, 4, v1
	v_lshrrev_b32_e32 v3, 7, v182
	v_bfe_u32 v4, v182, 5, 1
	v_lshlrev_b32_e32 v3, 6, v3
	v_lshl_or_b32 v3, v4, 2, v3
	v_mul_u32_u24_e32 v3, 136, v3
	v_and_b32_e32 v4, 0x5f, v182
	v_add_lshl_u32 v0, v3, v4, 1
	s_barrier
	ds_write_b16 v0, v190
	ds_write_b16_d16_hi v0, v190 offset:272
	ds_write_b16 v0, v191 offset:544
	ds_write_b16_d16_hi v0, v191 offset:816
	ds_write_b16 v0, v192 offset:2176
	ds_write_b16_d16_hi v0, v192 offset:2448
	ds_write_b16 v0, v193 offset:2720
	ds_write_b16_d16_hi v0, v193 offset:2992
	ds_write_b16 v0, v194 offset:4352
	ds_write_b16_d16_hi v0, v194 offset:4624
	ds_write_b16 v0, v195 offset:4896
	ds_write_b16_d16_hi v0, v195 offset:5168
	ds_write_b16 v0, v196 offset:6528
	ds_write_b16_d16_hi v0, v196 offset:6800
	ds_write_b16 v0, v197 offset:7072
	ds_write_b16_d16_hi v0, v197 offset:7344
	ds_write_b16 v0, v198 offset:64
	ds_write_b16_d16_hi v0, v198 offset:336
	ds_write_b16 v0, v199 offset:608
	ds_write_b16_d16_hi v0, v199 offset:880
	ds_write_b16 v0, v200 offset:2240
	ds_write_b16_d16_hi v0, v200 offset:2512
	ds_write_b16 v0, v201 offset:2784
	ds_write_b16_d16_hi v0, v201 offset:3056
	ds_write_b16 v0, v202 offset:4416
	ds_write_b16_d16_hi v0, v202 offset:4688
	ds_write_b16 v0, v203 offset:4960
	ds_write_b16_d16_hi v0, v203 offset:5232
	ds_write_b16 v0, v204 offset:6592
	ds_write_b16_d16_hi v0, v204 offset:6864
	ds_write_b16 v0, v205 offset:7136
	ds_write_b16_d16_hi v0, v205 offset:7408
	ds_write_b16 v0, v206 offset:8704
	ds_write_b16_d16_hi v0, v206 offset:8976
	ds_write_b16 v0, v207 offset:9248
	ds_write_b16_d16_hi v0, v207 offset:9520
	ds_write_b16 v0, v208 offset:10880
	ds_write_b16_d16_hi v0, v208 offset:11152
	ds_write_b16 v0, v209 offset:11424
	ds_write_b16_d16_hi v0, v209 offset:11696
	ds_write_b16 v0, v210 offset:13056
	ds_write_b16_d16_hi v0, v210 offset:13328
	ds_write_b16 v0, v211 offset:13600
	ds_write_b16_d16_hi v0, v211 offset:13872
	ds_write_b16 v0, v212 offset:15232
	ds_write_b16_d16_hi v0, v212 offset:15504
	ds_write_b16 v0, v213 offset:15776
	ds_write_b16_d16_hi v0, v213 offset:16048
	ds_write_b16 v0, v214 offset:8768
	ds_write_b16_d16_hi v0, v214 offset:9040
	ds_write_b16 v0, v215 offset:9312
	ds_write_b16_d16_hi v0, v215 offset:9584
	ds_write_b16 v0, v216 offset:10944
	ds_write_b16_d16_hi v0, v216 offset:11216
	ds_write_b16 v0, v217 offset:11488
	ds_write_b16_d16_hi v0, v217 offset:11760
	ds_write_b16 v0, v218 offset:13120
	ds_write_b16_d16_hi v0, v218 offset:13392
	ds_write_b16 v0, v219 offset:13664
	ds_write_b16_d16_hi v0, v219 offset:13936
	ds_write_b16 v0, v220 offset:15296
	ds_write_b16_d16_hi v0, v220 offset:15568
	ds_write_b16 v0, v221 offset:15840
	ds_write_b16_d16_hi v0, v221 offset:16112
	s_waitcnt lgkmcnt(0)
	s_barrier
	ds_read_b128 v[8:11], v1
	ds_read_b128 v[12:15], v1 offset:4352
	ds_read_b128 v[16:19], v1 offset:8704
	ds_read_b128 v[20:23], v1 offset:13056
	ds_read_b128 v[24:27], v1 offset:17408
	ds_read_b128 v[28:31], v1 offset:21760
	ds_read_b128 v[32:35], v1 offset:26112
	ds_read_b128 v[36:39], v1 offset:30464
	s_add_u32 s38, s44, 0x0
	s_addc_u32 s39, s45, 0
	s_waitcnt lgkmcnt(7)
	global_store_dwordx4 v2, v[8:11], s[38:39]
	s_add_u32 s38, s44, 0x20000
	s_addc_u32 s39, s45, 0
	s_waitcnt lgkmcnt(6)
	global_store_dwordx4 v2, v[12:15], s[38:39]
	s_add_u32 s38, s44, 0x40000
	s_addc_u32 s39, s45, 0
	s_waitcnt lgkmcnt(5)
	global_store_dwordx4 v2, v[16:19], s[38:39]
	s_add_u32 s38, s44, 0x60000
	s_addc_u32 s39, s45, 0
	s_waitcnt lgkmcnt(4)
	global_store_dwordx4 v2, v[20:23], s[38:39]
	s_add_u32 s38, s44, 0x100000
	s_addc_u32 s39, s45, 0
	s_waitcnt lgkmcnt(3)
	global_store_dwordx4 v2, v[24:27], s[38:39]
	s_add_u32 s38, s44, 0x120000
	s_addc_u32 s39, s45, 0
	s_waitcnt lgkmcnt(2)
	global_store_dwordx4 v2, v[28:31], s[38:39]
	s_add_u32 s38, s44, 0x140000
	s_addc_u32 s39, s45, 0
	s_waitcnt lgkmcnt(1)
	global_store_dwordx4 v2, v[32:35], s[38:39]
	s_add_u32 s38, s44, 0x160000
	s_addc_u32 s39, s45, 0
	s_waitcnt lgkmcnt(0)
	global_store_dwordx4 v2, v[36:39], s[38:39]
	s_barrier
	ds_write_b16 v0, v222
	ds_write_b16_d16_hi v0, v222 offset:272
	ds_write_b16 v0, v223 offset:544
	ds_write_b16_d16_hi v0, v223 offset:816
	ds_write_b16 v0, v224 offset:2176
	ds_write_b16_d16_hi v0, v224 offset:2448
	ds_write_b16 v0, v225 offset:2720
	ds_write_b16_d16_hi v0, v225 offset:2992
	ds_write_b16 v0, v226 offset:4352
	ds_write_b16_d16_hi v0, v226 offset:4624
	ds_write_b16 v0, v227 offset:4896
	ds_write_b16_d16_hi v0, v227 offset:5168
	ds_write_b16 v0, v228 offset:6528
	ds_write_b16_d16_hi v0, v228 offset:6800
	ds_write_b16 v0, v229 offset:7072
	ds_write_b16_d16_hi v0, v229 offset:7344
	ds_write_b16 v0, v230 offset:64
	ds_write_b16_d16_hi v0, v230 offset:336
	ds_write_b16 v0, v231 offset:608
	ds_write_b16_d16_hi v0, v231 offset:880
	ds_write_b16 v0, v232 offset:2240
	ds_write_b16_d16_hi v0, v232 offset:2512
	ds_write_b16 v0, v233 offset:2784
	ds_write_b16_d16_hi v0, v233 offset:3056
	ds_write_b16 v0, v234 offset:4416
	ds_write_b16_d16_hi v0, v234 offset:4688
	ds_write_b16 v0, v235 offset:4960
	ds_write_b16_d16_hi v0, v235 offset:5232
	ds_write_b16 v0, v236 offset:6592
	ds_write_b16_d16_hi v0, v236 offset:6864
	ds_write_b16 v0, v237 offset:7136
	ds_write_b16_d16_hi v0, v237 offset:7408
	ds_write_b16 v0, v238 offset:8704
	ds_write_b16_d16_hi v0, v238 offset:8976
	ds_write_b16 v0, v239 offset:9248
	ds_write_b16_d16_hi v0, v239 offset:9520
	ds_write_b16 v0, v240 offset:10880
	ds_write_b16_d16_hi v0, v240 offset:11152
	ds_write_b16 v0, v241 offset:11424
	ds_write_b16_d16_hi v0, v241 offset:11696
	ds_write_b16 v0, v242 offset:13056
	ds_write_b16_d16_hi v0, v242 offset:13328
	ds_write_b16 v0, v243 offset:13600
	ds_write_b16_d16_hi v0, v243 offset:13872
	ds_write_b16 v0, v244 offset:15232
	ds_write_b16_d16_hi v0, v244 offset:15504
	ds_write_b16 v0, v245 offset:15776
	ds_write_b16_d16_hi v0, v245 offset:16048
	ds_write_b16 v0, v246 offset:8768
	ds_write_b16_d16_hi v0, v246 offset:9040
	ds_write_b16 v0, v247 offset:9312
	ds_write_b16_d16_hi v0, v247 offset:9584
	ds_write_b16 v0, v248 offset:10944
	ds_write_b16_d16_hi v0, v248 offset:11216
	ds_write_b16 v0, v249 offset:11488
	ds_write_b16_d16_hi v0, v249 offset:11760
	ds_write_b16 v0, v250 offset:13120
	ds_write_b16_d16_hi v0, v250 offset:13392
	ds_write_b16 v0, v251 offset:13664
	ds_write_b16_d16_hi v0, v251 offset:13936
	ds_write_b16 v0, v252 offset:15296
	ds_write_b16_d16_hi v0, v252 offset:15568
	ds_write_b16 v0, v253 offset:15840
	ds_write_b16_d16_hi v0, v253 offset:16112
	s_waitcnt lgkmcnt(0)
	s_barrier
	ds_read_b128 v[8:11], v1
	ds_read_b128 v[12:15], v1 offset:4352
	ds_read_b128 v[16:19], v1 offset:8704
	ds_read_b128 v[20:23], v1 offset:13056
	ds_read_b128 v[24:27], v1 offset:17408
	ds_read_b128 v[28:31], v1 offset:21760
	ds_read_b128 v[32:35], v1 offset:26112
	ds_read_b128 v[36:39], v1 offset:30464
	s_add_u32 s38, s44, 0x80000
	s_addc_u32 s39, s45, 0
	s_waitcnt lgkmcnt(7)
	global_store_dwordx4 v2, v[8:11], s[38:39]
	s_add_u32 s38, s44, 0xa0000
	s_addc_u32 s39, s45, 0
	s_waitcnt lgkmcnt(6)
	global_store_dwordx4 v2, v[12:15], s[38:39]
	s_add_u32 s38, s44, 0xc0000
	s_addc_u32 s39, s45, 0
	s_waitcnt lgkmcnt(5)
	global_store_dwordx4 v2, v[16:19], s[38:39]
	s_add_u32 s38, s44, 0xe0000
	s_addc_u32 s39, s45, 0
	s_waitcnt lgkmcnt(4)
	global_store_dwordx4 v2, v[20:23], s[38:39]
	s_add_u32 s38, s44, 0x180000
	s_addc_u32 s39, s45, 0
	s_waitcnt lgkmcnt(3)
	global_store_dwordx4 v2, v[24:27], s[38:39]
	s_add_u32 s38, s44, 0x1a0000
	s_addc_u32 s39, s45, 0
	s_waitcnt lgkmcnt(2)
	global_store_dwordx4 v2, v[28:31], s[38:39]
	s_add_u32 s38, s44, 0x1c0000
	s_addc_u32 s39, s45, 0
	s_waitcnt lgkmcnt(1)
	global_store_dwordx4 v2, v[32:35], s[38:39]
	s_add_u32 s38, s44, 0x1e0000
	s_addc_u32 s39, s45, 0
	s_waitcnt lgkmcnt(0)
	global_store_dwordx4 v2, v[36:39], s[38:39]
	v_mov_b32_e32 v0, 0
	v_mov_b32_e32 v1, 0
	v_mov_b32_e32 v2, 0
	v_mov_b32_e32 v3, 0
	v_mov_b32_e32 v4, 0
	v_mov_b32_e32 v5, 0
	v_mov_b32_e32 v6, 0
	v_mov_b32_e32 v7, 0
	v_mov_b32_e32 v8, 0
	v_mov_b32_e32 v9, 0
	v_mov_b32_e32 v10, 0
	v_mov_b32_e32 v11, 0
	v_mov_b32_e32 v12, 0
	v_mov_b32_e32 v13, 0
	v_mov_b32_e32 v14, 0
	v_mov_b32_e32 v15, 0
	v_mov_b32_e32 v16, 0
	v_mov_b32_e32 v17, 0
	v_mov_b32_e32 v18, 0
	v_mov_b32_e32 v19, 0
	v_mov_b32_e32 v20, 0
	v_mov_b32_e32 v21, 0
	v_mov_b32_e32 v22, 0
	v_mov_b32_e32 v23, 0
	v_mov_b32_e32 v24, 0
	v_mov_b32_e32 v25, 0
	v_mov_b32_e32 v26, 0
	v_mov_b32_e32 v27, 0
	v_mov_b32_e32 v28, 0
	v_mov_b32_e32 v29, 0
	v_mov_b32_e32 v30, 0
	v_mov_b32_e32 v31, 0
	v_mov_b32_e32 v32, 0
	v_mov_b32_e32 v33, 0
	v_mov_b32_e32 v34, 0
	v_mov_b32_e32 v35, 0
	v_mov_b32_e32 v36, 0
	v_mov_b32_e32 v37, 0
	v_mov_b32_e32 v38, 0
	v_mov_b32_e32 v39, 0

.LBB0_1977:
	ds_read_b128 v[216:219], v188 offset:36864
	ds_read_b128 v[200:203], v187
	ds_read_b128 v[220:223], v188 offset:41472
	ds_read_b128 v[204:207], v187 offset:4608
	ds_read_b128 v[208:211], v187 offset:9216
	ds_read_b128 v[212:215], v176
	s_waitcnt lgkmcnt(4)
	v_mfma_f32_32x32x16_bf16 v[112:127], v[200:203], v[216:219], v[112:127]
	ds_read_b128 v[240:243], v188 offset:36896
	global_load_dwordx4 v[160:163], v190, s[38:39]
	s_waitcnt lgkmcnt(4)
	v_mfma_f32_32x32x16_bf16 v[96:111], v[200:203], v[220:223], v[96:111]
	ds_read_b128 v[224:227], v187 offset:32
	global_load_dwordx4 v[128:131], v191, s[38:39]
	s_waitcnt lgkmcnt(4)
	v_mfma_f32_32x32x16_bf16 v[80:95], v[204:207], v[216:219], v[80:95]
	ds_read_b128 v[244:247], v188 offset:41504
	global_load_dwordx4 v[132:135], v192, s[38:39]
	s_waitcnt lgkmcnt(5)
	v_mfma_f32_32x32x16_bf16 v[64:79], v[204:207], v[220:223], v[64:79]
	ds_read_b128 v[228:231], v187 offset:4640
	global_load_dwordx4 v[136:139], v193, s[38:39]
	s_waitcnt lgkmcnt(5)
	v_mfma_f32_32x32x16_bf16 v[48:63], v[208:211], v[216:219], v[48:63]
	ds_read_b128 v[232:235], v187 offset:9248
	global_load_dwordx4 v[140:143], v194, s[38:39]
	s_waitcnt lgkmcnt(6)
	v_mfma_f32_32x32x16_bf16 v[32:47], v[208:211], v[220:223], v[32:47]
	ds_read_b128 v[236:239], v176 offset:32
	global_load_dwordx4 v[144:147], v195, s[38:39]
	s_waitcnt lgkmcnt(6)
	v_mfma_f32_32x32x16_bf16 v[16:31], v[212:215], v[216:219], v[16:31]
	global_load_dwordx4 v[148:151], v196, s[38:39]
	global_load_dwordx4 v[156:159], v197, s[38:39]
	s_waitcnt lgkmcnt(6)
	v_mfma_f32_32x32x16_bf16 v[0:15], v[212:215], v[220:223], v[0:15]
	global_load_dwordx4 v[152:155], v190, s[40:41]
	global_load_dwordx4 v[164:167], v191, s[40:41]
	s_waitcnt lgkmcnt(4)
	v_mfma_f32_32x32x16_bf16 v[112:127], v[224:227], v[240:243], v[112:127]
	ds_read_b128 v[200:203], v187 offset:64
	global_load_dwordx4 v[168:171], v192, s[40:41]
	s_waitcnt lgkmcnt(4)
	v_mfma_f32_32x32x16_bf16 v[96:111], v[224:227], v[244:247], v[96:111]
	ds_read_b128 v[204:207], v187 offset:4672
	global_load_dwordx4 v[172:175], v193, s[40:41]
	s_add_u32 s38, s38, 0x80
	s_addc_u32 s39, s39, 0
	s_add_u32 s40, s40, 0x80
	s_addc_u32 s41, s41, 0
	s_add_u32 s12, s12, 0x80
	s_waitcnt lgkmcnt(4)
	v_mfma_f32_32x32x16_bf16 v[80:95], v[228:231], v[240:243], v[80:95]
	ds_read_b128 v[208:211], v187 offset:9280
	s_waitcnt lgkmcnt(5)
	v_mfma_f32_32x32x16_bf16 v[64:79], v[228:231], v[244:247], v[64:79]
	ds_read_b128 v[212:215], v176 offset:64
	s_waitcnt lgkmcnt(5)
	v_mfma_f32_32x32x16_bf16 v[48:63], v[232:235], v[240:243], v[48:63]
	ds_read_b128 v[216:219], v188 offset:36928
	s_waitcnt lgkmcnt(6)
	v_mfma_f32_32x32x16_bf16 v[32:47], v[232:235], v[244:247], v[32:47]
	ds_read_b128 v[220:223], v188 offset:41536
	s_waitcnt lgkmcnt(6)
	v_mfma_f32_32x32x16_bf16 v[16:31], v[236:239], v[240:243], v[16:31]
	s_waitcnt lgkmcnt(6)
	v_mfma_f32_32x32x16_bf16 v[0:15], v[236:239], v[244:247], v[0:15]
	s_waitcnt lgkmcnt(1)
	v_mfma_f32_32x32x16_bf16 v[112:127], v[200:203], v[216:219], v[112:127]
	ds_read_b128 v[224:227], v187 offset:96
	s_waitcnt lgkmcnt(1)
	v_mfma_f32_32x32x16_bf16 v[96:111], v[200:203], v[220:223], v[96:111]
	ds_read_b128 v[228:231], v187 offset:4704
	s_waitcnt lgkmcnt(3)
	v_mfma_f32_32x32x16_bf16 v[80:95], v[204:207], v[216:219], v[80:95]
	ds_read_b128 v[232:235], v187 offset:9312
	s_waitcnt lgkmcnt(3)
	v_mfma_f32_32x32x16_bf16 v[64:79], v[204:207], v[220:223], v[64:79]
	ds_read_b128 v[236:239], v176 offset:96
	s_waitcnt lgkmcnt(5)
	v_mfma_f32_32x32x16_bf16 v[48:63], v[208:211], v[216:219], v[48:63]
	ds_read_b128 v[240:243], v188 offset:36960
	s_waitcnt lgkmcnt(5)
	v_mfma_f32_32x32x16_bf16 v[32:47], v[208:211], v[220:223], v[32:47]
	ds_read_b128 v[244:247], v188 offset:41568
	s_waitcnt lgkmcnt(7)
	v_mfma_f32_32x32x16_bf16 v[16:31], v[212:215], v[216:219], v[16:31]
	s_waitcnt lgkmcnt(6)
	v_mfma_f32_32x32x16_bf16 v[0:15], v[212:215], v[220:223], v[0:15]
	s_waitcnt lgkmcnt(0)
	s_barrier
	s_waitcnt vmcnt(0)
	s_waitcnt lgkmcnt(1)
	v_mfma_f32_32x32x16_bf16 v[112:127], v[224:227], v[240:243], v[112:127]
	ds_write_b128 v189, v[160:163]
	ds_write_b128 v189, v[128:131] offset:4608
	s_waitcnt lgkmcnt(2)
	v_mfma_f32_32x32x16_bf16 v[96:111], v[224:227], v[244:247], v[96:111]
	ds_write_b128 v189, v[132:135] offset:9216
	s_waitcnt lgkmcnt(4)
	v_mfma_f32_32x32x16_bf16 v[80:95], v[228:231], v[240:243], v[80:95]
	ds_write_b128 v189, v[136:139] offset:13824
	ds_write_b128 v189, v[140:143] offset:18432
	s_waitcnt lgkmcnt(5)
	v_mfma_f32_32x32x16_bf16 v[64:79], v[228:231], v[244:247], v[64:79]
	ds_write_b128 v189, v[144:147] offset:23040
	s_waitcnt lgkmcnt(7)
	v_mfma_f32_32x32x16_bf16 v[48:63], v[232:235], v[240:243], v[48:63]
	ds_write_b128 v189, v[148:151] offset:27648
	ds_write_b128 v189, v[156:159] offset:32256
	s_waitcnt lgkmcnt(8)
	v_mfma_f32_32x32x16_bf16 v[32:47], v[232:235], v[244:247], v[32:47]
	ds_write_b128 v189, v[152:155] offset:36864
	s_waitcnt lgkmcnt(10)
	v_mfma_f32_32x32x16_bf16 v[16:31], v[236:239], v[240:243], v[16:31]
	ds_write_b128 v189, v[164:167] offset:41472
	ds_write_b128 v189, v[168:171] offset:46080
	s_waitcnt lgkmcnt(11)
	v_mfma_f32_32x32x16_bf16 v[0:15], v[236:239], v[244:247], v[0:15]
	ds_write_b128 v189, v[172:175] offset:50688
	s_waitcnt lgkmcnt(0)
	s_barrier
	s_cmpk_lg_i32 s12, 0x780
	s_cbranch_scc1 .LBB0_1977
	ds_read_b128 v[216:219], v188 offset:36864
	ds_read_b128 v[200:203], v187
	ds_read_b128 v[220:223], v188 offset:41472
	ds_read_b128 v[204:207], v187 offset:4608
	ds_read_b128 v[208:211], v187 offset:9216
	ds_read_b128 v[212:215], v176
	s_waitcnt lgkmcnt(4)
	v_mfma_f32_32x32x16_bf16 v[112:127], v[200:203], v[216:219], v[112:127]
	ds_read_b128 v[240:243], v188 offset:36896
	s_waitcnt lgkmcnt(4)
	v_mfma_f32_32x32x16_bf16 v[96:111], v[200:203], v[220:223], v[96:111]
	ds_read_b128 v[224:227], v187 offset:32
	s_waitcnt lgkmcnt(4)
	v_mfma_f32_32x32x16_bf16 v[80:95], v[204:207], v[216:219], v[80:95]
	ds_read_b128 v[244:247], v188 offset:41504
	s_waitcnt lgkmcnt(5)
	v_mfma_f32_32x32x16_bf16 v[64:79], v[204:207], v[220:223], v[64:79]
	ds_read_b128 v[228:231], v187 offset:4640
	s_waitcnt lgkmcnt(5)
	v_mfma_f32_32x32x16_bf16 v[48:63], v[208:211], v[216:219], v[48:63]
	ds_read_b128 v[232:235], v187 offset:9248
	s_waitcnt lgkmcnt(6)
	v_mfma_f32_32x32x16_bf16 v[32:47], v[208:211], v[220:223], v[32:47]
	ds_read_b128 v[236:239], v176 offset:32
	s_waitcnt lgkmcnt(6)
	v_mfma_f32_32x32x16_bf16 v[16:31], v[212:215], v[216:219], v[16:31]
	s_waitcnt lgkmcnt(6)
	v_mfma_f32_32x32x16_bf16 v[0:15], v[212:215], v[220:223], v[0:15]
	s_waitcnt lgkmcnt(4)
	v_mfma_f32_32x32x16_bf16 v[112:127], v[224:227], v[240:243], v[112:127]
	ds_read_b128 v[200:203], v187 offset:64
	s_waitcnt lgkmcnt(4)
	v_mfma_f32_32x32x16_bf16 v[96:111], v[224:227], v[244:247], v[96:111]
	ds_read_b128 v[204:207], v187 offset:4672
	s_waitcnt lgkmcnt(4)
	v_mfma_f32_32x32x16_bf16 v[80:95], v[228:231], v[240:243], v[80:95]
	ds_read_b128 v[208:211], v187 offset:9280
	s_waitcnt lgkmcnt(5)
	v_mfma_f32_32x32x16_bf16 v[64:79], v[228:231], v[244:247], v[64:79]
	ds_read_b128 v[212:215], v176 offset:64
	s_waitcnt lgkmcnt(5)
	v_mfma_f32_32x32x16_bf16 v[48:63], v[232:235], v[240:243], v[48:63]
	ds_read_b128 v[216:219], v188 offset:36928
	s_waitcnt lgkmcnt(6)
	v_mfma_f32_32x32x16_bf16 v[32:47], v[232:235], v[244:247], v[32:47]
	ds_read_b128 v[220:223], v188 offset:41536
	s_waitcnt lgkmcnt(6)
	v_mfma_f32_32x32x16_bf16 v[16:31], v[236:239], v[240:243], v[16:31]
	s_waitcnt lgkmcnt(6)
	v_mfma_f32_32x32x16_bf16 v[0:15], v[236:239], v[244:247], v[0:15]
	s_waitcnt lgkmcnt(1)
	v_mfma_f32_32x32x16_bf16 v[112:127], v[200:203], v[216:219], v[112:127]
	ds_read_b128 v[224:227], v187 offset:96
	s_waitcnt lgkmcnt(1)
	v_mfma_f32_32x32x16_bf16 v[96:111], v[200:203], v[220:223], v[96:111]
	ds_read_b128 v[228:231], v187 offset:4704
	s_waitcnt lgkmcnt(3)
	v_mfma_f32_32x32x16_bf16 v[80:95], v[204:207], v[216:219], v[80:95]
	ds_read_b128 v[232:235], v187 offset:9312
	s_waitcnt lgkmcnt(3)
	v_mfma_f32_32x32x16_bf16 v[64:79], v[204:207], v[220:223], v[64:79]
	ds_read_b128 v[236:239], v176 offset:96
	s_waitcnt lgkmcnt(5)
	v_mfma_f32_32x32x16_bf16 v[48:63], v[208:211], v[216:219], v[48:63]
	ds_read_b128 v[240:243], v188 offset:36960
	s_waitcnt lgkmcnt(5)
	v_mfma_f32_32x32x16_bf16 v[32:47], v[208:211], v[220:223], v[32:47]
	ds_read_b128 v[244:247], v188 offset:41568
	s_waitcnt lgkmcnt(7)
	v_mfma_f32_32x32x16_bf16 v[16:31], v[212:215], v[216:219], v[16:31]
	s_waitcnt lgkmcnt(6)
	v_mfma_f32_32x32x16_bf16 v[0:15], v[212:215], v[220:223], v[0:15]
	s_waitcnt lgkmcnt(1)
	v_mfma_f32_32x32x16_bf16 v[112:127], v[224:227], v[240:243], v[112:127]
	s_waitcnt lgkmcnt(0)
	v_mfma_f32_32x32x16_bf16 v[96:111], v[224:227], v[244:247], v[96:111]
	s_waitcnt lgkmcnt(1)
	v_mfma_f32_32x32x16_bf16 v[80:95], v[228:231], v[240:243], v[80:95]
	s_waitcnt lgkmcnt(0)
	v_mfma_f32_32x32x16_bf16 v[64:79], v[228:231], v[244:247], v[64:79]
	s_waitcnt lgkmcnt(1)
	v_mfma_f32_32x32x16_bf16 v[48:63], v[232:235], v[240:243], v[48:63]
	s_waitcnt lgkmcnt(0)
	v_mfma_f32_32x32x16_bf16 v[32:47], v[232:235], v[244:247], v[32:47]
	s_waitcnt lgkmcnt(1)
	v_mfma_f32_32x32x16_bf16 v[16:31], v[236:239], v[240:243], v[16:31]
	s_waitcnt lgkmcnt(0)
	v_mfma_f32_32x32x16_bf16 v[0:15], v[236:239], v[244:247], v[0:15]
	s_mul_i32 s42, s6, 0x2000
	s_add_u32 s44, s30, s42
	s_addc_u32 s45, s31, 0
	s_lshl_b32 s42, s58, 1
	s_add_u32 s44, s44, s42
	s_addc_u32 s45, s45, 0
	s_add_u32 s44, s44, 0x7157900
	s_addc_u32 s45, s45, 0
	s_mov_b32 s43, 1
	v_max_f32_e32 v112, 0, v112
	v_max_f32_e32 v113, 0, v113
	v_mul_f32_e32 v112, v112, v112
	v_mul_f32_e32 v113, v113, v113
	v_cvt_pk_bf16_f32 v190, v112, v113
	v_max_f32_e32 v114, 0, v114
	v_max_f32_e32 v115, 0, v115
	v_mul_f32_e32 v114, v114, v114
	v_mul_f32_e32 v115, v115, v115
	v_cvt_pk_bf16_f32 v191, v114, v115
	v_max_f32_e32 v116, 0, v116
	v_max_f32_e32 v117, 0, v117
	v_mul_f32_e32 v116, v116, v116
	v_mul_f32_e32 v117, v117, v117
	v_cvt_pk_bf16_f32 v192, v116, v117
	v_max_f32_e32 v118, 0, v118
	v_max_f32_e32 v119, 0, v119
	v_mul_f32_e32 v118, v118, v118
	v_mul_f32_e32 v119, v119, v119
	v_cvt_pk_bf16_f32 v193, v118, v119
	v_max_f32_e32 v120, 0, v120
	v_max_f32_e32 v121, 0, v121
	v_mul_f32_e32 v120, v120, v120
	v_mul_f32_e32 v121, v121, v121
	v_cvt_pk_bf16_f32 v194, v120, v121
	v_max_f32_e32 v122, 0, v122
	v_max_f32_e32 v123, 0, v123
	v_mul_f32_e32 v122, v122, v122
	v_mul_f32_e32 v123, v123, v123
	v_cvt_pk_bf16_f32 v195, v122, v123
	v_max_f32_e32 v124, 0, v124
	v_max_f32_e32 v125, 0, v125
	v_mul_f32_e32 v124, v124, v124
	v_mul_f32_e32 v125, v125, v125
	v_cvt_pk_bf16_f32 v196, v124, v125
	v_max_f32_e32 v126, 0, v126
	v_max_f32_e32 v127, 0, v127
	v_mul_f32_e32 v126, v126, v126
	v_mul_f32_e32 v127, v127, v127
	v_cvt_pk_bf16_f32 v197, v126, v127
	v_max_f32_e32 v96, 0, v96
	v_max_f32_e32 v97, 0, v97
	v_mul_f32_e32 v96, v96, v96
	v_mul_f32_e32 v97, v97, v97
	v_cvt_pk_bf16_f32 v198, v96, v97
	v_max_f32_e32 v98, 0, v98
	v_max_f32_e32 v99, 0, v99
	v_mul_f32_e32 v98, v98, v98
	v_mul_f32_e32 v99, v99, v99
	v_cvt_pk_bf16_f32 v199, v98, v99
	v_max_f32_e32 v100, 0, v100
	v_max_f32_e32 v101, 0, v101
	v_mul_f32_e32 v100, v100, v100
	v_mul_f32_e32 v101, v101, v101
	v_cvt_pk_bf16_f32 v200, v100, v101
	v_max_f32_e32 v102, 0, v102
	v_max_f32_e32 v103, 0, v103
	v_mul_f32_e32 v102, v102, v102
	v_mul_f32_e32 v103, v103, v103
	v_cvt_pk_bf16_f32 v201, v102, v103
	v_max_f32_e32 v104, 0, v104
	v_max_f32_e32 v105, 0, v105
	v_mul_f32_e32 v104, v104, v104
	v_mul_f32_e32 v105, v105, v105
	v_cvt_pk_bf16_f32 v202, v104, v105
	v_max_f32_e32 v106, 0, v106
	v_max_f32_e32 v107, 0, v107
	v_mul_f32_e32 v106, v106, v106
	v_mul_f32_e32 v107, v107, v107
	v_cvt_pk_bf16_f32 v203, v106, v107
	v_max_f32_e32 v108, 0, v108
	v_max_f32_e32 v109, 0, v109
	v_mul_f32_e32 v108, v108, v108
	v_mul_f32_e32 v109, v109, v109
	v_cvt_pk_bf16_f32 v204, v108, v109
	v_max_f32_e32 v110, 0, v110
	v_max_f32_e32 v111, 0, v111
	v_mul_f32_e32 v110, v110, v110
	v_mul_f32_e32 v111, v111, v111
	v_cvt_pk_bf16_f32 v205, v110, v111
	v_max_f32_e32 v80, 0, v80
	v_max_f32_e32 v81, 0, v81
	v_mul_f32_e32 v80, v80, v80
	v_mul_f32_e32 v81, v81, v81
	v_cvt_pk_bf16_f32 v206, v80, v81
	v_max_f32_e32 v82, 0, v82
	v_max_f32_e32 v83, 0, v83
	v_mul_f32_e32 v82, v82, v82
	v_mul_f32_e32 v83, v83, v83
	v_cvt_pk_bf16_f32 v207, v82, v83
	v_max_f32_e32 v84, 0, v84
	v_max_f32_e32 v85, 0, v85
	v_mul_f32_e32 v84, v84, v84
	v_mul_f32_e32 v85, v85, v85
	v_cvt_pk_bf16_f32 v208, v84, v85
	v_max_f32_e32 v86, 0, v86
	v_max_f32_e32 v87, 0, v87
	v_mul_f32_e32 v86, v86, v86
	v_mul_f32_e32 v87, v87, v87
	v_cvt_pk_bf16_f32 v209, v86, v87
	v_max_f32_e32 v88, 0, v88
	v_max_f32_e32 v89, 0, v89
	v_mul_f32_e32 v88, v88, v88
	v_mul_f32_e32 v89, v89, v89
	v_cvt_pk_bf16_f32 v210, v88, v89
	v_max_f32_e32 v90, 0, v90
	v_max_f32_e32 v91, 0, v91
	v_mul_f32_e32 v90, v90, v90
	v_mul_f32_e32 v91, v91, v91
	v_cvt_pk_bf16_f32 v211, v90, v91
	v_max_f32_e32 v92, 0, v92
	v_max_f32_e32 v93, 0, v93
	v_mul_f32_e32 v92, v92, v92
	v_mul_f32_e32 v93, v93, v93
	v_cvt_pk_bf16_f32 v212, v92, v93
	v_max_f32_e32 v94, 0, v94
	v_max_f32_e32 v95, 0, v95
	v_mul_f32_e32 v94, v94, v94
	v_mul_f32_e32 v95, v95, v95
	v_cvt_pk_bf16_f32 v213, v94, v95
	v_max_f32_e32 v64, 0, v64
	v_max_f32_e32 v65, 0, v65
	v_mul_f32_e32 v64, v64, v64
	v_mul_f32_e32 v65, v65, v65
	v_cvt_pk_bf16_f32 v214, v64, v65
	v_max_f32_e32 v66, 0, v66
	v_max_f32_e32 v67, 0, v67
	v_mul_f32_e32 v66, v66, v66
	v_mul_f32_e32 v67, v67, v67
	v_cvt_pk_bf16_f32 v215, v66, v67
	v_max_f32_e32 v68, 0, v68
	v_max_f32_e32 v69, 0, v69
	v_mul_f32_e32 v68, v68, v68
	v_mul_f32_e32 v69, v69, v69
	v_cvt_pk_bf16_f32 v216, v68, v69
	v_max_f32_e32 v70, 0, v70
	v_max_f32_e32 v71, 0, v71
	v_mul_f32_e32 v70, v70, v70
	v_mul_f32_e32 v71, v71, v71
	v_cvt_pk_bf16_f32 v217, v70, v71
	v_max_f32_e32 v72, 0, v72
	v_max_f32_e32 v73, 0, v73
	v_mul_f32_e32 v72, v72, v72
	v_mul_f32_e32 v73, v73, v73
	v_cvt_pk_bf16_f32 v218, v72, v73
	v_max_f32_e32 v74, 0, v74
	v_max_f32_e32 v75, 0, v75
	v_mul_f32_e32 v74, v74, v74
	v_mul_f32_e32 v75, v75, v75
	v_cvt_pk_bf16_f32 v219, v74, v75
	v_max_f32_e32 v76, 0, v76
	v_max_f32_e32 v77, 0, v77
	v_mul_f32_e32 v76, v76, v76
	v_mul_f32_e32 v77, v77, v77
	v_cvt_pk_bf16_f32 v220, v76, v77
	v_max_f32_e32 v78, 0, v78
	v_max_f32_e32 v79, 0, v79
	v_mul_f32_e32 v78, v78, v78
	v_mul_f32_e32 v79, v79, v79
	v_cvt_pk_bf16_f32 v221, v78, v79
	v_max_f32_e32 v48, 0, v48
	v_max_f32_e32 v49, 0, v49
	v_mul_f32_e32 v48, v48, v48
	v_mul_f32_e32 v49, v49, v49
	v_cvt_pk_bf16_f32 v222, v48, v49
	v_max_f32_e32 v50, 0, v50
	v_max_f32_e32 v51, 0, v51
	v_mul_f32_e32 v50, v50, v50
	v_mul_f32_e32 v51, v51, v51
	v_cvt_pk_bf16_f32 v223, v50, v51
	v_max_f32_e32 v52, 0, v52
	v_max_f32_e32 v53, 0, v53
	v_mul_f32_e32 v52, v52, v52
	v_mul_f32_e32 v53, v53, v53
	v_cvt_pk_bf16_f32 v224, v52, v53
	v_max_f32_e32 v54, 0, v54
	v_max_f32_e32 v55, 0, v55
	v_mul_f32_e32 v54, v54, v54
	v_mul_f32_e32 v55, v55, v55
	v_cvt_pk_bf16_f32 v225, v54, v55
	v_max_f32_e32 v56, 0, v56
	v_max_f32_e32 v57, 0, v57
	v_mul_f32_e32 v56, v56, v56
	v_mul_f32_e32 v57, v57, v57
	v_cvt_pk_bf16_f32 v226, v56, v57
	v_max_f32_e32 v58, 0, v58
	v_max_f32_e32 v59, 0, v59
	v_mul_f32_e32 v58, v58, v58
	v_mul_f32_e32 v59, v59, v59
	v_cvt_pk_bf16_f32 v227, v58, v59
	v_max_f32_e32 v60, 0, v60
	v_max_f32_e32 v61, 0, v61
	v_mul_f32_e32 v60, v60, v60
	v_mul_f32_e32 v61, v61, v61
	v_cvt_pk_bf16_f32 v228, v60, v61
	v_max_f32_e32 v62, 0, v62
	v_max_f32_e32 v63, 0, v63
	v_mul_f32_e32 v62, v62, v62
	v_mul_f32_e32 v63, v63, v63
	v_cvt_pk_bf16_f32 v229, v62, v63
	v_max_f32_e32 v32, 0, v32
	v_max_f32_e32 v33, 0, v33
	v_mul_f32_e32 v32, v32, v32
	v_mul_f32_e32 v33, v33, v33
	v_cvt_pk_bf16_f32 v230, v32, v33
	v_max_f32_e32 v34, 0, v34
	v_max_f32_e32 v35, 0, v35
	v_mul_f32_e32 v34, v34, v34
	v_mul_f32_e32 v35, v35, v35
	v_cvt_pk_bf16_f32 v231, v34, v35
	v_max_f32_e32 v36, 0, v36
	v_max_f32_e32 v37, 0, v37
	v_mul_f32_e32 v36, v36, v36
	v_mul_f32_e32 v37, v37, v37
	v_cvt_pk_bf16_f32 v232, v36, v37
	v_max_f32_e32 v38, 0, v38
	v_max_f32_e32 v39, 0, v39
	v_mul_f32_e32 v38, v38, v38
	v_mul_f32_e32 v39, v39, v39
	v_cvt_pk_bf16_f32 v233, v38, v39
	v_max_f32_e32 v40, 0, v40
	v_max_f32_e32 v41, 0, v41
	v_mul_f32_e32 v40, v40, v40
	v_mul_f32_e32 v41, v41, v41
	v_cvt_pk_bf16_f32 v234, v40, v41
	v_max_f32_e32 v42, 0, v42
	v_max_f32_e32 v43, 0, v43
	v_mul_f32_e32 v42, v42, v42
	v_mul_f32_e32 v43, v43, v43
	v_cvt_pk_bf16_f32 v235, v42, v43
	v_max_f32_e32 v44, 0, v44
	v_max_f32_e32 v45, 0, v45
	v_mul_f32_e32 v44, v44, v44
	v_mul_f32_e32 v45, v45, v45
	v_cvt_pk_bf16_f32 v236, v44, v45
	v_max_f32_e32 v46, 0, v46
	v_max_f32_e32 v47, 0, v47
	v_mul_f32_e32 v46, v46, v46
	v_mul_f32_e32 v47, v47, v47
	v_cvt_pk_bf16_f32 v237, v46, v47
	v_max_f32_e32 v16, 0, v16
	v_max_f32_e32 v17, 0, v17
	v_mul_f32_e32 v16, v16, v16
	v_mul_f32_e32 v17, v17, v17
	v_cvt_pk_bf16_f32 v238, v16, v17
	v_max_f32_e32 v18, 0, v18
	v_max_f32_e32 v19, 0, v19
	v_mul_f32_e32 v18, v18, v18
	v_mul_f32_e32 v19, v19, v19
	v_cvt_pk_bf16_f32 v239, v18, v19
	v_max_f32_e32 v20, 0, v20
	v_max_f32_e32 v21, 0, v21
	v_mul_f32_e32 v20, v20, v20
	v_mul_f32_e32 v21, v21, v21
	v_cvt_pk_bf16_f32 v240, v20, v21
	v_max_f32_e32 v22, 0, v22
	v_max_f32_e32 v23, 0, v23
	v_mul_f32_e32 v22, v22, v22
	v_mul_f32_e32 v23, v23, v23
	v_cvt_pk_bf16_f32 v241, v22, v23
	v_max_f32_e32 v24, 0, v24
	v_max_f32_e32 v25, 0, v25
	v_mul_f32_e32 v24, v24, v24
	v_mul_f32_e32 v25, v25, v25
	v_cvt_pk_bf16_f32 v242, v24, v25
	v_max_f32_e32 v26, 0, v26
	v_max_f32_e32 v27, 0, v27
	v_mul_f32_e32 v26, v26, v26
	v_mul_f32_e32 v27, v27, v27
	v_cvt_pk_bf16_f32 v243, v26, v27
	v_max_f32_e32 v28, 0, v28
	v_max_f32_e32 v29, 0, v29
	v_mul_f32_e32 v28, v28, v28
	v_mul_f32_e32 v29, v29, v29
	v_cvt_pk_bf16_f32 v244, v28, v29
	v_max_f32_e32 v30, 0, v30
	v_max_f32_e32 v31, 0, v31
	v_mul_f32_e32 v30, v30, v30
	v_mul_f32_e32 v31, v31, v31
	v_cvt_pk_bf16_f32 v245, v30, v31
	v_max_f32_e32 v0, 0, v0
	v_max_f32_e32 v1, 0, v1
	v_mul_f32_e32 v0, v0, v0
	v_mul_f32_e32 v1, v1, v1
	v_cvt_pk_bf16_f32 v246, v0, v1
	v_max_f32_e32 v2, 0, v2
	v_max_f32_e32 v3, 0, v3
	v_mul_f32_e32 v2, v2, v2
	v_mul_f32_e32 v3, v3, v3
	v_cvt_pk_bf16_f32 v247, v2, v3
	v_max_f32_e32 v4, 0, v4
	v_max_f32_e32 v5, 0, v5
	v_mul_f32_e32 v4, v4, v4
	v_mul_f32_e32 v5, v5, v5
	v_cvt_pk_bf16_f32 v248, v4, v5
	v_max_f32_e32 v6, 0, v6
	v_max_f32_e32 v7, 0, v7
	v_mul_f32_e32 v6, v6, v6
	v_mul_f32_e32 v7, v7, v7
	v_cvt_pk_bf16_f32 v249, v6, v7
	v_max_f32_e32 v8, 0, v8
	v_max_f32_e32 v9, 0, v9
	v_mul_f32_e32 v8, v8, v8
	v_mul_f32_e32 v9, v9, v9
	v_cvt_pk_bf16_f32 v250, v8, v9
	v_max_f32_e32 v10, 0, v10
	v_max_f32_e32 v11, 0, v11
	v_mul_f32_e32 v10, v10, v10
	v_mul_f32_e32 v11, v11, v11
	v_cvt_pk_bf16_f32 v251, v10, v11
	v_max_f32_e32 v12, 0, v12
	v_max_f32_e32 v13, 0, v13
	v_mul_f32_e32 v12, v12, v12
	v_mul_f32_e32 v13, v13, v13
	v_cvt_pk_bf16_f32 v252, v12, v13
	v_max_f32_e32 v14, 0, v14
	v_max_f32_e32 v15, 0, v15
	v_mul_f32_e32 v14, v14, v14
	v_mul_f32_e32 v15, v15, v15
	v_cvt_pk_bf16_f32 v253, v14, v15
	s_add_i32 s57, s57, s21
	s_add_i32 s56, s56, s21
	s_cmpk_lt_u32 s57, 0x200
	s_cbranch_scc1 .LBB0_1976
	v_and_b32_e32 v3, 15, v182
	v_lshrrev_b32_e32 v4, 4, v182
	v_mul_u32_u24_e32 v2, 0x2000, v4
	v_lshl_add_u32 v2, v3, 4, v2
	v_mul_u32_u24_e32 v1, 0x110, v4
	v_lshl_add_u32 v1, v3, 4, v1
	v_lshrrev_b32_e32 v3, 7, v182
	v_bfe_u32 v4, v182, 5, 1
	v_lshlrev_b32_e32 v3, 6, v3
	v_lshl_or_b32 v3, v4, 2, v3
	v_mul_u32_u24_e32 v3, 136, v3
	v_and_b32_e32 v4, 0x5f, v182
	v_add_lshl_u32 v0, v3, v4, 1
	s_barrier
	ds_write_b16 v0, v190
	ds_write_b16_d16_hi v0, v190 offset:272
	ds_write_b16 v0, v191 offset:544
	ds_write_b16_d16_hi v0, v191 offset:816
	ds_write_b16 v0, v192 offset:2176
	ds_write_b16_d16_hi v0, v192 offset:2448
	ds_write_b16 v0, v193 offset:2720
	ds_write_b16_d16_hi v0, v193 offset:2992
	ds_write_b16 v0, v194 offset:4352
	ds_write_b16_d16_hi v0, v194 offset:4624
	ds_write_b16 v0, v195 offset:4896
	ds_write_b16_d16_hi v0, v195 offset:5168
	ds_write_b16 v0, v196 offset:6528
	ds_write_b16_d16_hi v0, v196 offset:6800
	ds_write_b16 v0, v197 offset:7072
	ds_write_b16_d16_hi v0, v197 offset:7344
	ds_write_b16 v0, v198 offset:64
	ds_write_b16_d16_hi v0, v198 offset:336
	ds_write_b16 v0, v199 offset:608
	ds_write_b16_d16_hi v0, v199 offset:880
	ds_write_b16 v0, v200 offset:2240
	ds_write_b16_d16_hi v0, v200 offset:2512
	ds_write_b16 v0, v201 offset:2784
	ds_write_b16_d16_hi v0, v201 offset:3056
	ds_write_b16 v0, v202 offset:4416
	ds_write_b16_d16_hi v0, v202 offset:4688
	ds_write_b16 v0, v203 offset:4960
	ds_write_b16_d16_hi v0, v203 offset:5232
	ds_write_b16 v0, v204 offset:6592
	ds_write_b16_d16_hi v0, v204 offset:6864
	ds_write_b16 v0, v205 offset:7136
	ds_write_b16_d16_hi v0, v205 offset:7408
	ds_write_b16 v0, v206 offset:8704
	ds_write_b16_d16_hi v0, v206 offset:8976
	ds_write_b16 v0, v207 offset:9248
	ds_write_b16_d16_hi v0, v207 offset:9520
	ds_write_b16 v0, v208 offset:10880
	ds_write_b16_d16_hi v0, v208 offset:11152
	ds_write_b16 v0, v209 offset:11424
	ds_write_b16_d16_hi v0, v209 offset:11696
	ds_write_b16 v0, v210 offset:13056
	ds_write_b16_d16_hi v0, v210 offset:13328
	ds_write_b16 v0, v211 offset:13600
	ds_write_b16_d16_hi v0, v211 offset:13872
	ds_write_b16 v0, v212 offset:15232
	ds_write_b16_d16_hi v0, v212 offset:15504
	ds_write_b16 v0, v213 offset:15776
	ds_write_b16_d16_hi v0, v213 offset:16048
	ds_write_b16 v0, v214 offset:8768
	ds_write_b16_d16_hi v0, v214 offset:9040
	ds_write_b16 v0, v215 offset:9312
	ds_write_b16_d16_hi v0, v215 offset:9584
	ds_write_b16 v0, v216 offset:10944
	ds_write_b16_d16_hi v0, v216 offset:11216
	ds_write_b16 v0, v217 offset:11488
	ds_write_b16_d16_hi v0, v217 offset:11760
	ds_write_b16 v0, v218 offset:13120
	ds_write_b16_d16_hi v0, v218 offset:13392
	ds_write_b16 v0, v219 offset:13664
	ds_write_b16_d16_hi v0, v219 offset:13936
	ds_write_b16 v0, v220 offset:15296
	ds_write_b16_d16_hi v0, v220 offset:15568
	ds_write_b16 v0, v221 offset:15840
	ds_write_b16_d16_hi v0, v221 offset:16112
	s_waitcnt lgkmcnt(0)
	s_barrier
	ds_read_b128 v[8:11], v1
	ds_read_b128 v[12:15], v1 offset:4352
	ds_read_b128 v[16:19], v1 offset:8704
	ds_read_b128 v[20:23], v1 offset:13056
	ds_read_b128 v[24:27], v1 offset:17408
	ds_read_b128 v[28:31], v1 offset:21760
	ds_read_b128 v[32:35], v1 offset:26112
	ds_read_b128 v[36:39], v1 offset:30464
	s_add_u32 s38, s44, 0x0
	s_addc_u32 s39, s45, 0
	s_waitcnt lgkmcnt(7)
	global_store_dwordx4 v2, v[8:11], s[38:39]
	s_add_u32 s38, s44, 0x20000
	s_addc_u32 s39, s45, 0
	s_waitcnt lgkmcnt(6)
	global_store_dwordx4 v2, v[12:15], s[38:39]
	s_add_u32 s38, s44, 0x40000
	s_addc_u32 s39, s45, 0
	s_waitcnt lgkmcnt(5)
	global_store_dwordx4 v2, v[16:19], s[38:39]
	s_add_u32 s38, s44, 0x60000
	s_addc_u32 s39, s45, 0
	s_waitcnt lgkmcnt(4)
	global_store_dwordx4 v2, v[20:23], s[38:39]
	s_add_u32 s38, s44, 0x100000
	s_addc_u32 s39, s45, 0
	s_waitcnt lgkmcnt(3)
	global_store_dwordx4 v2, v[24:27], s[38:39]
	s_add_u32 s38, s44, 0x120000
	s_addc_u32 s39, s45, 0
	s_waitcnt lgkmcnt(2)
	global_store_dwordx4 v2, v[28:31], s[38:39]
	s_add_u32 s38, s44, 0x140000
	s_addc_u32 s39, s45, 0
	s_waitcnt lgkmcnt(1)
	global_store_dwordx4 v2, v[32:35], s[38:39]
	s_add_u32 s38, s44, 0x160000
	s_addc_u32 s39, s45, 0
	s_waitcnt lgkmcnt(0)
	global_store_dwordx4 v2, v[36:39], s[38:39]
	s_barrier
	ds_write_b16 v0, v222
	ds_write_b16_d16_hi v0, v222 offset:272
	ds_write_b16 v0, v223 offset:544
	ds_write_b16_d16_hi v0, v223 offset:816
	ds_write_b16 v0, v224 offset:2176
	ds_write_b16_d16_hi v0, v224 offset:2448
	ds_write_b16 v0, v225 offset:2720
	ds_write_b16_d16_hi v0, v225 offset:2992
	ds_write_b16 v0, v226 offset:4352
	ds_write_b16_d16_hi v0, v226 offset:4624
	ds_write_b16 v0, v227 offset:4896
	ds_write_b16_d16_hi v0, v227 offset:5168
	ds_write_b16 v0, v228 offset:6528
	ds_write_b16_d16_hi v0, v228 offset:6800
	ds_write_b16 v0, v229 offset:7072
	ds_write_b16_d16_hi v0, v229 offset:7344
	ds_write_b16 v0, v230 offset:64
	ds_write_b16_d16_hi v0, v230 offset:336
	ds_write_b16 v0, v231 offset:608
	ds_write_b16_d16_hi v0, v231 offset:880
	ds_write_b16 v0, v232 offset:2240
	ds_write_b16_d16_hi v0, v232 offset:2512
	ds_write_b16 v0, v233 offset:2784
	ds_write_b16_d16_hi v0, v233 offset:3056
	ds_write_b16 v0, v234 offset:4416
	ds_write_b16_d16_hi v0, v234 offset:4688
	ds_write_b16 v0, v235 offset:4960
	ds_write_b16_d16_hi v0, v235 offset:5232
	ds_write_b16 v0, v236 offset:6592
	ds_write_b16_d16_hi v0, v236 offset:6864
	ds_write_b16 v0, v237 offset:7136
	ds_write_b16_d16_hi v0, v237 offset:7408
	ds_write_b16 v0, v238 offset:8704
	ds_write_b16_d16_hi v0, v238 offset:8976
	ds_write_b16 v0, v239 offset:9248
	ds_write_b16_d16_hi v0, v239 offset:9520
	ds_write_b16 v0, v240 offset:10880
	ds_write_b16_d16_hi v0, v240 offset:11152
	ds_write_b16 v0, v241 offset:11424
	ds_write_b16_d16_hi v0, v241 offset:11696
	ds_write_b16 v0, v242 offset:13056
	ds_write_b16_d16_hi v0, v242 offset:13328
	ds_write_b16 v0, v243 offset:13600
	ds_write_b16_d16_hi v0, v243 offset:13872
	ds_write_b16 v0, v244 offset:15232
	ds_write_b16_d16_hi v0, v244 offset:15504
	ds_write_b16 v0, v245 offset:15776
	ds_write_b16_d16_hi v0, v245 offset:16048
	ds_write_b16 v0, v246 offset:8768
	ds_write_b16_d16_hi v0, v246 offset:9040
	ds_write_b16 v0, v247 offset:9312
	ds_write_b16_d16_hi v0, v247 offset:9584
	ds_write_b16 v0, v248 offset:10944
	ds_write_b16_d16_hi v0, v248 offset:11216
	ds_write_b16 v0, v249 offset:11488
	ds_write_b16_d16_hi v0, v249 offset:11760
	ds_write_b16 v0, v250 offset:13120
	ds_write_b16_d16_hi v0, v250 offset:13392
	ds_write_b16 v0, v251 offset:13664
	ds_write_b16_d16_hi v0, v251 offset:13936
	ds_write_b16 v0, v252 offset:15296
	ds_write_b16_d16_hi v0, v252 offset:15568
	ds_write_b16 v0, v253 offset:15840
	ds_write_b16_d16_hi v0, v253 offset:16112
	s_waitcnt lgkmcnt(0)
	s_barrier
	ds_read_b128 v[8:11], v1
	ds_read_b128 v[12:15], v1 offset:4352
	ds_read_b128 v[16:19], v1 offset:8704
	ds_read_b128 v[20:23], v1 offset:13056
	ds_read_b128 v[24:27], v1 offset:17408
	ds_read_b128 v[28:31], v1 offset:21760
	ds_read_b128 v[32:35], v1 offset:26112
	ds_read_b128 v[36:39], v1 offset:30464
	s_add_u32 s38, s44, 0x80000
	s_addc_u32 s39, s45, 0
	s_waitcnt lgkmcnt(7)
	global_store_dwordx4 v2, v[8:11], s[38:39]
	s_add_u32 s38, s44, 0xa0000
	s_addc_u32 s39, s45, 0
	s_waitcnt lgkmcnt(6)
	global_store_dwordx4 v2, v[12:15], s[38:39]
	s_add_u32 s38, s44, 0xc0000
	s_addc_u32 s39, s45, 0
	s_waitcnt lgkmcnt(5)
	global_store_dwordx4 v2, v[16:19], s[38:39]
	s_add_u32 s38, s44, 0xe0000
	s_addc_u32 s39, s45, 0
	s_waitcnt lgkmcnt(4)
	global_store_dwordx4 v2, v[20:23], s[38:39]
	s_add_u32 s38, s44, 0x180000
	s_addc_u32 s39, s45, 0
	s_waitcnt lgkmcnt(3)
	global_store_dwordx4 v2, v[24:27], s[38:39]
	s_add_u32 s38, s44, 0x1a0000
	s_addc_u32 s39, s45, 0
	s_waitcnt lgkmcnt(2)
	global_store_dwordx4 v2, v[28:31], s[38:39]
	s_add_u32 s38, s44, 0x1c0000
	s_addc_u32 s39, s45, 0
	s_waitcnt lgkmcnt(1)
	global_store_dwordx4 v2, v[32:35], s[38:39]
	s_add_u32 s38, s44, 0x1e0000
	s_addc_u32 s39, s45, 0
	s_waitcnt lgkmcnt(0)
	global_store_dwordx4 v2, v[36:39], s[38:39]
	s_mov_b32 s43, 0
	s_branch .LBB0_1969
